# P0 counted vmcnt + batched LDS transpose reads; SSD early Cm/Bm staging; attention QK^T read pipelining + early KV loads
# speedup vs baseline: 1.0045x; 1.0045x over previous
; #define LAS __attribute__((address_space(3)))
; #define LDS_WAIT() asm volatile("s_waitcnt lgkmcnt(0)" ::: "memory")
; __device__ __forceinline__ unsigned cvt_pk_bf16(float lo, float hi) { unsigned r; asm volatile("v_cvt_pk_bf16_f32 %0, %1, %2" : "=v"(r) : "v"(lo), "v"(hi)); return r; }
; __device__ __forceinline__ void titem_store(const TItem& t, f32x4 (&v)[8], LAS float* scr, int lane) {
;     const int kr = lane >> 3, col = (lane & 7) * 4;
;     if (t.kscale) {
; #pragma unroll
;         for (int i = 0; i < 8; ++i) v[i] *= t.kscale[8 * i + kr]; }
; #pragma unroll
;     for (int i = 0; i < 8; ++i) *(LAS f32x4*)(scr + (8 * i + kr) * 32 + ((col + 4 * i) & 31)) = v[i];
;     LDS_WAIT();
;     const int c = lane & 7;
; #pragma unroll
;     for (int j = 0; j < 4; ++j) { const int n = (lane >> 3) + 8 * j; const LAS float* s = scr + (8 * c) * 32 + ((n + 4 * c) & 31);
;         u32x4 o; o.x = cvt_pk_bf16(s[0 * 32], s[1 * 32]); o.y = cvt_pk_bf16(s[2 * 32], s[3 * 32]); o.z = cvt_pk_bf16(s[4 * 32], s[5 * 32]); o.w = cvt_pk_bf16(s[6 * 32], s[7 * 32]);
;         *(u32x4*)(t.dst + (size_t)n * t.ldt + 8 * c) = o; }
;     LDS_WAIT();
; }
.LBB0_55:
	v_mad_u64_u32 v[94:95], s[12:13], v66, s21, 0
	s_waitcnt vmcnt(19)
	ds_write_b128 v75, v[34:37]
	s_waitcnt vmcnt(18)
	ds_write_b128 v77, v[38:41] offset:1024
	s_waitcnt vmcnt(17)
	ds_write_b128 v78, v[42:45] offset:2048
	s_waitcnt vmcnt(16)
	ds_write_b128 v79, v[46:49] offset:3072
	s_waitcnt vmcnt(15)
	ds_write_b128 v80, v[50:53] offset:4096
	s_waitcnt vmcnt(14)
	ds_write_b128 v81, v[54:57] offset:5120
	s_waitcnt vmcnt(13)
	ds_write_b128 v82, v[58:61] offset:6144
	s_waitcnt vmcnt(12)
	ds_write_b128 v83, v[62:65] offset:7168
	v_mov_b32_e32 v96, v95
	s_waitcnt lgkmcnt(0)
	ds_read2_b32 v[104:105], v84 offset1:32
	ds_read2_b32 v[106:107], v84 offset0:64 offset1:96
	ds_read2_b32 v[108:109], v84 offset0:128 offset1:160
	ds_read2_b32 v[110:111], v84 offset0:192 offset1:224
	ds_read2_b32 v[112:113], v85 offset1:32
	ds_read2_b32 v[114:115], v85 offset0:64 offset1:96
	ds_read2_b32 v[116:117], v85 offset0:128 offset1:160
	ds_read2_b32 v[118:119], v85 offset0:192 offset1:224
	v_mad_u64_u32 v[96:97], s[12:13], v67, s21, v[96:97]
	v_mov_b32_e32 v95, v96
	s_waitcnt lgkmcnt(7)
	v_cvt_pk_bf16_f32 v88, v104, v105
	v_lshl_add_u64 v[94:95], v[94:95], 1, s[4:5]
	s_waitcnt lgkmcnt(6)
	v_cvt_pk_bf16_f32 v89, v106, v107
	v_lshl_add_u64 v[94:95], v[94:95], 0, v[70:71]
	s_waitcnt lgkmcnt(5)
	v_cvt_pk_bf16_f32 v90, v108, v109
	s_waitcnt lgkmcnt(4)
	v_cvt_pk_bf16_f32 v91, v110, v111
	ds_read2_b32 v[120:121], v86 offset1:32
	ds_read2_b32 v[122:123], v86 offset0:64 offset1:96
	ds_read2_b32 v[124:125], v86 offset0:128 offset1:160
	ds_read2_b32 v[126:127], v86 offset0:192 offset1:224
	ds_read2_b32 v[128:129], v87 offset1:32
	ds_read2_b32 v[130:131], v87 offset0:64 offset1:96
	ds_read2_b32 v[132:133], v87 offset0:128 offset1:160
	ds_read2_b32 v[134:135], v87 offset0:192 offset1:224
	global_store_dwordx4 v[94:95], v[88:91], off
	v_mad_u64_u32 v[94:95], s[12:13], v72, s21, 0
	v_mov_b32_e32 v96, v95
	v_mad_u64_u32 v[96:97], s[12:13], v1, s21, v[96:97]
	v_mov_b32_e32 v95, v96
	s_waitcnt lgkmcnt(11)
	v_cvt_pk_bf16_f32 v88, v112, v113
	v_lshl_add_u64 v[94:95], v[94:95], 1, s[4:5]
	s_waitcnt lgkmcnt(10)
	v_cvt_pk_bf16_f32 v89, v114, v115
	v_lshl_add_u64 v[94:95], v[94:95], 0, v[70:71]
	s_waitcnt lgkmcnt(9)
	v_cvt_pk_bf16_f32 v90, v116, v117
	s_waitcnt lgkmcnt(8)
	v_cvt_pk_bf16_f32 v91, v118, v119
	global_store_dwordx4 v[94:95], v[88:91], off
	v_mad_u64_u32 v[94:95], s[12:13], v74, s21, 0
	v_mov_b32_e32 v96, v95
	s_waitcnt lgkmcnt(7)
	v_cvt_pk_bf16_f32 v88, v120, v121
	v_mad_u64_u32 v[96:97], s[12:13], v69, s21, v[96:97]
	s_waitcnt lgkmcnt(6)
	v_cvt_pk_bf16_f32 v89, v122, v123
	v_mov_b32_e32 v95, v96
	s_waitcnt lgkmcnt(5)
	v_cvt_pk_bf16_f32 v90, v124, v125
	v_lshl_add_u64 v[94:95], v[94:95], 1, s[4:5]
	v_readlane_b32 s12, v254, 40
	s_waitcnt lgkmcnt(4)
	v_cvt_pk_bf16_f32 v91, v126, v127
	v_lshl_add_u64 v[94:95], v[94:95], 0, v[70:71]
	v_readlane_b32 s13, v254, 41
	global_store_dwordx4 v[94:95], v[88:91], off
	s_add_i32 s28, s26, s12
	s_add_i32 s22, s22, s23
	s_waitcnt lgkmcnt(3)
	v_cvt_pk_bf16_f32 v88, v128, v129
	v_mad_u64_u32 v[92:93], s[12:13], v76, s21, 0
	v_mov_b32_e32 v94, v93
	v_mad_u64_u32 v[94:95], s[12:13], v73, s21, v[94:95]
	v_mov_b32_e32 v93, v94
	v_lshl_add_u64 v[92:93], v[92:93], 1, s[4:5]
	s_waitcnt lgkmcnt(2)
	v_cvt_pk_bf16_f32 v89, v130, v131
	v_lshl_add_u64 v[92:93], v[92:93], 0, v[70:71]
	s_waitcnt lgkmcnt(1)
	v_cvt_pk_bf16_f32 v90, v132, v133
	s_waitcnt lgkmcnt(0)
	v_cvt_pk_bf16_f32 v91, v134, v135
	global_store_dwordx4 v[92:93], v[88:91], off
	s_waitcnt lgkmcnt(0)
	s_add_i32 s25, s25, s23
	s_cmp_gt_i32 s28, 0x25d3f
	s_cselect_b64 s[12:13], -1, 0

; #define LAS __attribute__((address_space(3)))
; #define LDS_WAIT() asm volatile("s_waitcnt lgkmcnt(0)" ::: "memory")
; __device__ __forceinline__ void titem_store(const TItem& t, f32x4 (&v)[8], LAS float* scr, int lane) {
;     const int kr = lane >> 3, col = (lane & 7) * 4;
;     if (t.kscale) {
; #pragma unroll
;         for (int i = 0; i < 8; ++i) v[i] *= t.kscale[8 * i + kr]; }
; #pragma unroll
;     for (int i = 0; i < 8; ++i) *(LAS f32x4*)(scr + (8 * i + kr) * 32 + ((col + 4 * i) & 31)) = v[i];
;     LDS_WAIT();
;     const int c = lane & 7;
; #pragma unroll
;     for (int j = 0; j < 4; ++j) { const int n = (lane >> 3) + 8 * j; const LAS float* s = scr + (8 * c) * 32 + ((n + 4 * c) & 31);
;         u32x4 o; o.x = cvt_pk_bf16(s[0 * 32], s[1 * 32]); o.y = cvt_pk_bf16(s[2 * 32], s[3 * 32]); o.z = cvt_pk_bf16(s[4 * 32], s[5 * 32]); o.w = cvt_pk_bf16(s[6 * 32], s[7 * 32]);
;         *(u32x4*)(t.dst + (size_t)n * t.ldt + 8 * c) = o; }
;     LDS_WAIT();
; }
; __device__ __forceinline__ TItem p0_item(Frame& F, int it) {
;     constexpr int I_IN = (D_MODEL / 64) * (NPROJ / 32), I_PS = (D_INNER / 64) * (D_MODEL / 32), I_PA = (D_ATT / 64) * (D_MODEL / 32), I_O = (D_MODEL / 64) * (D_MODEL / 32), I_UP = (D_MODEL / 64) * (2 * D_FF / 32);
;     int r = it; TItem t; t.kscale = nullptr;
;     if (r < I_IN) { const int nb = NPROJ / 32, kb = r / nb, n0 = (r % nb) * 32; t.N = NPROJ; t.src = F.w_in + (size_t)kb * 64 * NPROJ + n0; t.dst = F.WIN + (size_t)win_row(n0) * D_MODEL + kb * 64; t.ldt = D_MODEL; return t; } r -= I_IN;
;     if (r < I_PS) { const int nb = D_MODEL / 32, kb = r / nb, n0 = (r % nb) * 32; t.N = D_MODEL; t.src = F.w_pssd + (size_t)kb * 64 * D_MODEL + n0; t.dst = F.WP + (size_t)n0 * KM + kb * 64; t.ldt = KM; t.kscale = F.norm_w + kb * 64; return t; } r -= I_PS;
;     if (r < I_PA) { const int nb = D_MODEL / 32, kb = r / nb, n0 = (r % nb) * 32; t.N = D_MODEL; t.src = F.w_patt + (size_t)kb * 64 * D_MODEL + n0; t.dst = F.WP + (size_t)n0 * KM + D_INNER + kb * 64; t.ldt = KM; return t; } r -= I_PA;
;     if (r < I_O) { const int nb = D_MODEL / 32, kb = r / nb, n0 = (r % nb) * 32; t.N = D_MODEL; t.src = F.w_out + (size_t)kb * 64 * D_MODEL + n0; t.dst = F.WO + (size_t)n0 * D_MODEL + kb * 64; t.ldt = D_MODEL; return t; } r -= I_O;
.LBB0_93:
	v_mad_u64_u32 v[94:95], s[14:15], v66, s27, 0
	s_waitcnt vmcnt(15)
	ds_write_b128 v75, v[2:5]
	s_waitcnt vmcnt(14)
	ds_write_b128 v77, v[6:9] offset:1024
	s_waitcnt vmcnt(13)
	ds_write_b128 v78, v[10:13] offset:2048
	s_waitcnt vmcnt(12)
	ds_write_b128 v79, v[14:17] offset:3072
	s_waitcnt vmcnt(11)
	ds_write_b128 v80, v[18:21] offset:4096
	s_waitcnt vmcnt(10)
	ds_write_b128 v81, v[22:25] offset:5120
	s_waitcnt vmcnt(9)
	ds_write_b128 v82, v[26:29] offset:6144
	s_waitcnt vmcnt(8)
	ds_write_b128 v83, v[30:33] offset:7168
	v_mov_b32_e32 v96, v95
	s_waitcnt lgkmcnt(0)
	ds_read2_b32 v[104:105], v84 offset1:32
	ds_read2_b32 v[106:107], v84 offset0:64 offset1:96
	ds_read2_b32 v[108:109], v84 offset0:128 offset1:160
	ds_read2_b32 v[110:111], v84 offset0:192 offset1:224
	ds_read2_b32 v[112:113], v85 offset1:32
	ds_read2_b32 v[114:115], v85 offset0:64 offset1:96
	ds_read2_b32 v[116:117], v85 offset0:128 offset1:160
	ds_read2_b32 v[118:119], v85 offset0:192 offset1:224
	v_mad_u64_u32 v[96:97], s[14:15], v67, s27, v[96:97]
	v_mov_b32_e32 v95, v96
	s_waitcnt lgkmcnt(7)
	v_cvt_pk_bf16_f32 v88, v104, v105
	v_lshl_add_u64 v[94:95], v[94:95], 1, s[8:9]
	s_waitcnt lgkmcnt(6)
	v_cvt_pk_bf16_f32 v89, v106, v107
	v_lshl_add_u64 v[94:95], v[94:95], 0, v[70:71]
	s_waitcnt lgkmcnt(5)
	v_cvt_pk_bf16_f32 v90, v108, v109
	s_waitcnt lgkmcnt(4)
	v_cvt_pk_bf16_f32 v91, v110, v111
	ds_read2_b32 v[120:121], v86 offset1:32
	ds_read2_b32 v[122:123], v86 offset0:64 offset1:96
	ds_read2_b32 v[124:125], v86 offset0:128 offset1:160
	ds_read2_b32 v[126:127], v86 offset0:192 offset1:224
	ds_read2_b32 v[128:129], v87 offset1:32
	ds_read2_b32 v[130:131], v87 offset0:64 offset1:96
	ds_read2_b32 v[132:133], v87 offset0:128 offset1:160
	ds_read2_b32 v[134:135], v87 offset0:192 offset1:224
	global_store_dwordx4 v[94:95], v[88:91], off
	v_mad_u64_u32 v[94:95], s[14:15], v72, s27, 0
	v_mov_b32_e32 v96, v95
	v_mad_u64_u32 v[96:97], s[14:15], v1, s27, v[96:97]
	v_mov_b32_e32 v95, v96
	s_waitcnt lgkmcnt(11)
	v_cvt_pk_bf16_f32 v88, v112, v113
	v_lshl_add_u64 v[94:95], v[94:95], 1, s[8:9]
	s_waitcnt lgkmcnt(10)
	v_cvt_pk_bf16_f32 v89, v114, v115
	v_lshl_add_u64 v[94:95], v[94:95], 0, v[70:71]
	s_waitcnt lgkmcnt(9)
	v_cvt_pk_bf16_f32 v90, v116, v117
	s_waitcnt lgkmcnt(8)
	v_cvt_pk_bf16_f32 v91, v118, v119
	global_store_dwordx4 v[94:95], v[88:91], off
	v_mad_u64_u32 v[94:95], s[14:15], v74, s27, 0
	v_mov_b32_e32 v96, v95
	s_waitcnt lgkmcnt(7)
	v_cvt_pk_bf16_f32 v88, v120, v121
	v_mad_u64_u32 v[96:97], s[14:15], v69, s27, v[96:97]
	s_waitcnt lgkmcnt(6)
	v_cvt_pk_bf16_f32 v89, v122, v123
	v_mov_b32_e32 v95, v96
	s_waitcnt lgkmcnt(5)
	v_cvt_pk_bf16_f32 v90, v124, v125
	v_lshl_add_u64 v[94:95], v[94:95], 1, s[8:9]
	s_waitcnt lgkmcnt(4)
	v_cvt_pk_bf16_f32 v91, v126, v127
	v_lshl_add_u64 v[94:95], v[94:95], 0, v[70:71]
	global_store_dwordx4 v[94:95], v[88:91], off
	s_andn2_b64 vcc, exec, s[12:13]
	s_mov_b64 s[12:13], -1
	s_waitcnt lgkmcnt(3)
	v_cvt_pk_bf16_f32 v88, v128, v129
	v_mad_u64_u32 v[92:93], s[14:15], v76, s27, 0
	v_mov_b32_e32 v94, v93
	v_mad_u64_u32 v[94:95], s[14:15], v73, s27, v[94:95]
	v_mov_b32_e32 v93, v94
	v_lshl_add_u64 v[92:93], v[92:93], 1, s[8:9]
	s_waitcnt lgkmcnt(2)
	v_cvt_pk_bf16_f32 v89, v130, v131
	v_lshl_add_u64 v[92:93], v[92:93], 0, v[70:71]
	s_waitcnt lgkmcnt(1)
	v_cvt_pk_bf16_f32 v90, v132, v133
	s_waitcnt lgkmcnt(0)
	v_cvt_pk_bf16_f32 v91, v134, v135
	global_store_dwordx4 v[92:93], v[88:91], off
	s_waitcnt lgkmcnt(0)
	s_cbranch_vccnz .LBB0_56
	s_add_i32 s18, s24, s28
	s_cmp_gt_i32 s18, 0x25d3f
	s_cbranch_scc1 .Lmy_p0_dumA
	s_cmp_gt_i32 s18, 0x1313f
	s_mov_b64 s[16:17], -1
	s_cbranch_scc0 .LBB0_112
	s_cmp_gt_u32 s18, 0x1713f
	s_mov_b64 s[10:11], -1
	s_cbranch_scc0 .LBB0_110
	s_cmp_gt_u32 s18, 0x1913f
	s_cbranch_scc0 .LBB0_107
	s_cmp_gt_u32 s18, 0x1b13f
	s_cbranch_scc0 .LBB0_104
	s_add_i32 s2, s18, 0x4ec0
	s_and_b32 s8, s2, 0xffff
	s_mul_i32 s8, s8, 0xbe83
	s_lshr_b32 s11, s8, 25
	s_mul_i32 s8, s11, 0x2b0
	s_sub_i32 s2, s2, s8
	s_and_b32 s2, s2, 0xffff
	s_lshl_b32 s10, s2, 5
	s_lshl_b32 s12, s2, 6
	s_cmpk_gt_u32 s2, 0x157
	s_mov_b64 s[8:9], -1
	s_cbranch_scc0 .LBB0_101
	s_add_i32 s2, s12, 0x7fffaa00
	s_and_b32 s2, s2, 0x7fffff00
	s_and_b32 s8, s10, 0x60
	s_or_b32 s2, s8, s2
	s_bitset1_b32 s2, 7
	s_mov_b64 s[8:9], 0

; __device__ __forceinline__ void convert_items(Frame& F, int first, int end, int w, int nw) {
;     ...
;     if (it < end) titem_load(ta, va, F.lane);
;     while (it < end) {
;         const int it1 = it + nw, it2 = it1 + nw;
;         if (it1 < end) { tb = p0_item(F, it1); titem_load(tb, vb, F.lane); }
;         titem_store(ta, va, scr, F.lane);
;         if (it1 >= end) break;
;         if (it2 < end) { ta = p0_item(F, it2); titem_load(ta, va, F.lane); }
;         titem_store(tb, vb, scr, F.lane);
;         it = it2;
;     }
.Lmy_p0_dumB:
	global_load_dwordx4 v[34:37], v71, s[96:97]
	global_load_dwordx4 v[38:41], v71, s[96:97]
	global_load_dwordx4 v[42:45], v71, s[96:97]
	global_load_dwordx4 v[46:49], v71, s[96:97]
	global_load_dwordx4 v[50:53], v71, s[96:97]
	global_load_dwordx4 v[54:57], v71, s[96:97]
	global_load_dwordx4 v[58:61], v71, s[96:97]
	global_load_dwordx4 v[62:65], v71, s[96:97]
	s_branch .LBB0_91
.Lmy_p0_dumA:
	global_load_dwordx4 v[2:5], v71, s[96:97]
	global_load_dwordx4 v[6:9], v71, s[96:97]
	global_load_dwordx4 v[10:13], v71, s[96:97]
	global_load_dwordx4 v[14:17], v71, s[96:97]
	global_load_dwordx4 v[18:21], v71, s[96:97]
	global_load_dwordx4 v[22:25], v71, s[96:97]
	global_load_dwordx4 v[26:29], v71, s[96:97]
	global_load_dwordx4 v[30:33], v71, s[96:97]
	s_branch .LBB0_128

; __device__ __forceinline__ void loads(Pre& P, const bf16* XTh  , const bf16* BCg  , const float* SV, int c, int tid, int lane) {
;     const bf16* bc = BCg + (size_t)c * BCT_CHUNK + tid * 8;
;     P.pc[0] = *(const u32x4*)(bc + 8192); P.pc[1] = *(const u32x4*)(bc + 8192 + 4096);
;     P.pc[2] = *(const u32x4*)bc; P.pc[3] = *(const u32x4*)(bc + 4096);
;     P.pc[4] = *(const u32x4*)(bc + 16384); P.pc[5] = *(const u32x4*)(bc + 16384 + 4096);
;     P.pc[6] = *(const u32x4*)(XTh + (size_t)c * 4096 + tid * 8);
;     const float* sp = SV + (size_t)c * SSD_H * 256 + lane;
; #pragma unroll
;     for (int k = 0; k < 4; ++k) P.sv[k] = sp[64 * k];
; }
; __device__ __forceinline__ void phase(lptr lds, const bf16* Z, const bf16* XACT, const bf16* BCT, const float* DTV, const float* a_log, const float* dskip, bf16* AM, float* SSQ, int G, int bx) {
;     ...
;         const float dsk = dskip[h];
;         const size_t row0 = (size_t)b * SEQ;
;         const bf16* XSh = XACT + ((size_t)b * SSD_H + h) * SEQ * 64; const bf16* BCg = BCT + ((size_t)b * SSD_G + g) * 64 * BCT_CHUNK; const bf16* Zh = Z + ((size_t)b * SSD_H + h) * SEQ * 64;
;         const float* SVh = DTV + ((size_t)b * (SEQ / 64) * SSD_H + h) * 256;
;         f32x16 st = {};
;         Pre PA, PB;
;         loads(PA, XSh, BCg, SVh, 0, tid, lane); loads(PB, XSh, BCg, SVh, 1, tid, lane);
;         u32x2 znA[4], znB[4];
;         { const bf16* zp = Zh + (size_t)(32 * (wid & 1) + r32) * 64 + 32 * ((wid >> 1) & 1) + 4 * hi;
; #pragma unroll
;             for (int q = 0; q < 4; ++q) { znA[q] = *(const u32x2*)(zp + 8 * q); znB[q] = *(const u32x2*)(zp + 64 * 64 + 8 * q); } }
;         for (int c2 = 0; c2 < SEQ / 128; ++c2) {
; #pragma unroll
;         for (int hf = 0; hf < 2; ++hf) {
;             const int c = 2 * c2 + hf; Pre& P = hf ? PB : PA; u32x2 (&zn)[4] = hf ? znB : znA;
;             const size_t t0 = row0 + (size_t)c * 64;
;             stage_pieces(P, lds, tid);
.LBB0_409:
	s_ashr_i32 s33, s72, 31
	s_lshr_b32 s33, s33, 25
	s_add_i32 s33, s72, s33
	s_ashr_i32 s38, s33, 7
	s_and_b32 s33, s33, 0xffffff80
	s_sub_i32 s40, s72, s33
	s_bfe_i32 s33, s40, 0x80000
	s_bfe_u32 s33, s33, 0x4000b
	s_add_i32 s33, s40, s33
	s_ashr_i32 s41, s40, 31
	s_mov_b32 s39, s86
	v_readlane_b32 s80, v254, 4
	s_bfe_i32 s33, s33, 0x80000
	s_lshl_b64 s[42:43], s[40:41], 2
	v_readlane_b32 s92, v254, 16
	v_readlane_b32 s86, v254, 10
	v_readlane_b32 s93, v254, 17
	s_add_u32 s42, s92, s42
	s_mov_b32 s86, s39
	s_addc_u32 s43, s93, s43
	s_ashr_i32 s39, s38, 31
	global_load_dword v242, v3, s[42:43]
	s_lshl_b64 s[42:43], s[40:41], 18
	s_lshl_b64 s[70:71], s[38:39], 25
	s_add_u32 s42, s70, s42
	s_addc_u32 s43, s71, s43
	v_readlane_b32 s82, v254, 6
	s_lshl_b64 s[42:43], s[42:43], 1
	s_sext_i32_i16 s33, s33
	v_readlane_b32 s83, v254, 7
	s_add_u32 s82, s44, s42
	s_addc_u32 s83, s45, s43
	s_ashr_i32 s33, s33, 4
	s_mul_hi_i32 s71, s33, 0x300000
	s_mul_i32 s33, s33, 0x300000
	s_add_u32 s33, s48, s33
	v_readlane_b32 s84, v254, 8
	s_mul_i32 s70, s38, 0x1800000
	s_addc_u32 s71, s49, s71
	v_readlane_b32 s85, v254, 9
	s_mul_hi_i32 s52, s38, 0x1800000
	s_add_u32 s84, s33, s70
	s_addc_u32 s85, s71, s52
	v_lshl_add_u64 v[154:155], s[84:85], 0, v[146:147]
	v_add_co_u32_e32 v4, vcc, s76, v154
	s_add_u32 s42, s46, s42
	s_nop 0
	v_addc_co_u32_e32 v5, vcc, 0, v155, vcc
	v_add_co_u32_e32 v6, vcc, s75, v154
	s_addc_u32 s43, s47, s43
	s_nop 0
	v_addc_co_u32_e32 v7, vcc, 0, v155, vcc
	global_load_dwordx4 v[52:55], v[4:5], off
	global_load_dwordx4 v[56:59], v[6:7], off
	v_add_co_u32_e32 v4, vcc, s77, v154
	s_lshl_b64 s[70:71], s[38:39], 23
	s_nop 0
	v_addc_co_u32_e32 v5, vcc, 0, v155, vcc
	v_add_co_u32_e32 v6, vcc, s78, v154
	s_add_u32 s33, s50, s70
	s_nop 0
	v_addc_co_u32_e32 v7, vcc, 0, v155, vcc
	s_addc_u32 s52, s51, s71
	s_lshl_b64 s[70:71], s[40:41], 10
	global_load_dwordx4 v[60:63], v[4:5], off
	global_load_dwordx4 v[68:71], v[6:7], off
	v_add_co_u32_e32 v4, vcc, s79, v154
	s_add_u32 s70, s33, s70
	s_nop 0
	v_addc_co_u32_e32 v5, vcc, 0, v155, vcc
	s_mov_b32 s33, 0x10000
	v_add_co_u32_e32 v6, vcc, s33, v154
	s_addc_u32 s71, s52, s71
	s_nop 0
	v_addc_co_u32_e32 v7, vcc, 0, v155, vcc
	s_mov_b32 s33, 0x12000
	v_lshl_add_u64 v[156:157], s[82:83], 0, v[146:147]
	global_load_dwordx4 v[64:67], v[154:155], off
	global_load_dwordx4 v[76:79], v[156:157], off
	global_load_dword v243, v148, s[70:71] offset:256
	global_load_dword v245, v148, s[70:71] offset:512
	global_load_dword v246, v148, s[70:71] offset:768
	global_load_dwordx4 v[80:83], v[4:5], off
	global_load_dwordx4 v[72:75], v[6:7], off
	v_add_co_u32_e32 v4, vcc, s33, v154
	s_mov_b32 s33, 0xc000
	s_nop 0
	v_addc_co_u32_e32 v5, vcc, 0, v155, vcc
	v_add_co_u32_e32 v6, vcc, s33, v154
	s_mov_b32 s33, 0xe000
	s_nop 0
	v_addc_co_u32_e32 v7, vcc, 0, v155, vcc
	global_load_dwordx4 v[88:91], v[4:5], off
	global_load_dwordx4 v[84:87], v[6:7], off
	v_add_co_u32_e32 v4, vcc, s33, v154
	s_mov_b32 s33, 0x14000
	s_nop 0
	v_addc_co_u32_e32 v5, vcc, 0, v155, vcc
	v_add_co_u32_e32 v6, vcc, s33, v154
	s_mov_b32 s33, 0x16000
	s_nop 0
	v_addc_co_u32_e32 v7, vcc, 0, v155, vcc
	global_load_dwordx4 v[92:95], v[4:5], off
	global_load_dwordx4 v[96:99], v[6:7], off
	v_add_co_u32_e32 v4, vcc, s33, v154
	v_lshl_add_u64 v[158:159], s[70:71], 0, v[148:149]
	s_nop 0
	v_addc_co_u32_e32 v5, vcc, 0, v155, vcc
	v_add_co_u32_e32 v6, vcc, s77, v156
	s_mov_b32 s33, 0x20000
	s_nop 0
	v_addc_co_u32_e32 v7, vcc, 0, v157, vcc
	v_lshl_add_u64 v[8:9], s[42:43], 0, v[150:151]
	global_load_dwordx4 v[100:103], v[4:5], off
	global_load_dwordx4 v[104:107], v[6:7], off
	v_add_co_u32_e32 v6, vcc, s33, v158
	v_lshl_add_u64 v[8:9], v[8:9], 0, s[68:69]
	v_lshl_add_u64 v[4:5], v[158:159], 0, s[66:67]
	v_addc_co_u32_e32 v7, vcc, 0, v159, vcc
	v_lshl_add_u64 v[8:9], v[8:9], 0, v[152:153]
	global_load_dword v247, v[6:7], off
	global_load_dword v248, v[4:5], off offset:256
	global_load_dword v249, v[4:5], off offset:512
	global_load_dwordx2 v[214:215], v[8:9], off
	global_load_dword v250, v[4:5], off offset:768
	v_add_co_u32_e32 v4, vcc, s77, v8
	s_add_u32 s42, s42, s68
	s_nop 0
	v_addc_co_u32_e32 v5, vcc, 0, v9, vcc
	global_load_dwordx2 v[198:199], v[4:5], off
	global_load_dwordx2 v[212:213], v[8:9], off offset:16
	global_load_dwordx2 v[210:211], v[8:9], off offset:32
	global_load_dwordx2 v[208:209], v[8:9], off offset:48
	global_load_dword v251, v148, s[70:71]
	global_load_dwordx2 v[196:197], v[4:5], off offset:16
	global_load_dwordx2 v[192:193], v[4:5], off offset:32
	global_load_dwordx2 v[188:189], v[4:5], off offset:48
	s_addc_u32 s43, s43, 0
	v_lshl_add_u64 v[160:161], s[42:43], 0, v[152:153]
	s_lshl_b32 s42, s40, 6
	s_lshl_b32 s40, s40, 1
	s_ashr_i32 s41, s40, 31
	s_ashr_i32 s43, s42, 31
	s_lshl_b64 s[70:71], s[38:39], 22
	s_lshl_b64 s[82:83], s[40:41], 2
	s_add_u32 s82, s82, s70
	s_addc_u32 s83, s83, s71
	s_mul_hi_i32 s33, s38, 0x6000000
	s_mul_i32 s52, s38, 0x6000000
	s_lshl_b64 s[38:39], s[42:43], 1
	s_add_u32 s38, s38, s52
	s_addc_u32 s39, s39, s33
	v_lshl_add_u64 v[164:165], s[38:39], 0, v[142:143]
	s_or_b64 s[38:39], s[54:55], s[40:41]
	s_lshl_b64 s[38:39], s[38:39], 2
	s_add_u32 s38, s38, s70
	v_mov_b32_e32 v4, v3
	v_mov_b32_e32 v5, v3
	v_mov_b32_e32 v6, v3
	v_mov_b32_e32 v7, v3
	v_mov_b32_e32 v8, v3
	v_mov_b32_e32 v9, v3
	v_mov_b32_e32 v10, v3
	v_mov_b32_e32 v11, v3
	v_mov_b32_e32 v12, v3
	v_mov_b32_e32 v13, v3
	v_mov_b32_e32 v14, v3
	v_mov_b32_e32 v15, v3
	v_mov_b32_e32 v16, v3
	v_mov_b32_e32 v17, v3
	v_readlane_b32 s81, v254, 5
	s_addc_u32 s39, s39, s71
	v_mov_b32_e32 v2, v3
	v_mov_b64_e32 v[18:19], v[16:17]
	v_lshl_add_u64 v[162:163], s[82:83], 0, v[140:141]
	v_lshl_add_u64 v[166:167], s[38:39], 0, v[144:145]
	s_mov_b32 s81, 3
	s_mov_b32 s82, s53
	v_mov_b64_e32 v[16:17], v[14:15]
	v_mov_b64_e32 v[14:15], v[12:13]
	v_mov_b64_e32 v[12:13], v[10:11]
	v_mov_b64_e32 v[10:11], v[8:9]
	v_mov_b64_e32 v[8:9], v[6:7]
	v_mov_b64_e32 v[6:7], v[4:5]
	v_mov_b64_e32 v[4:5], v[2:3]
	v_readlane_b32 s87, v254, 11
	v_readlane_b32 s88, v254, 12
	v_readlane_b32 s89, v254, 13
	v_readlane_b32 s90, v254, 14
	v_readlane_b32 s91, v254, 15
	v_readlane_b32 s94, v254, 18
	v_readlane_b32 s95, v254, 19
	s_waitcnt vmcnt(29)
	ds_write_b128 v235, v[52:55]
	s_waitcnt vmcnt(28)
	ds_write_b128 v235, v[56:59] offset:8704
	s_waitcnt vmcnt(25)
	ds_write_b128 v235, v[64:67] offset:17408
	ds_write_b128 v235, v[60:63] offset:26112
.LBB0_410:
	s_and_b64 vcc, exec, s[56:57]
	s_waitcnt vmcnt(25)
	ds_write_b128 v236, v[68:71] offset:34816
	s_waitcnt vmcnt(20)
	ds_write_b128 v236, v[80:83] offset:44032
	ds_write_b128 v236, v[76:79] offset:53248
	s_cbranch_vccz .LBB0_412
	s_waitcnt vmcnt(3)
	ds_write2st64_b32 v217, v251, v243 offset1:1
	ds_write2st64_b32 v217, v245, v246 offset0:2 offset1:3

; #define LAS __attribute__((address_space(3)))
; __device__ __forceinline__ void unpack8(const u32x4 w, float (&v)[8]) { v[0] = bf_lo(w.x); v[1] = bf_hi(w.x); v[2] = bf_lo(w.y); v[3] = bf_hi(w.y); v[4] = bf_lo(w.z); v[5] = bf_hi(w.z); v[6] = bf_lo(w.w); v[7] = bf_hi(w.w); }
; __device__ __forceinline__ bf16x8 pack8f(const float (&v)[8]) { u32x4 w = {cvt_pk_bf16(v[0], v[1]), cvt_pk_bf16(v[2], v[3]), cvt_pk_bf16(v[4], v[5]), cvt_pk_bf16(v[6], v[7])}; return *reinterpret_cast<bf16x8*>(&w); }
; __device__ __forceinline__ void state_update(f32x16& st, lptr lds, const LAS float* vec, int wid, int r32, int hi) {
;     const int nt = wid & 3, pt = wid >> 2; const float cdec = vec[V_E / 4 + 63];
; #pragma unroll
;     for (int r = 0; r < 16; ++r) st[r] *= cdec;
;     const lptr btrow = lds + O_BT + (32 * nt + r32) * PBT + hi * 16; const lptr xtrow = lds + O_XT + (32 * pt + r32) * PXT + hi * 16;
; #pragma unroll
;     for (int ks = 0; ks < 4; ++ks) { const u32x4 xr = *(const LAS u32x4*)(xtrow + ks * 32);
;         const f32x4 w0 = *(const LAS f32x4*)(vec + V_W / 4 + 16 * ks + 8 * hi), w1 = *(const LAS f32x4*)(vec + V_W / 4 + 16 * ks + 8 * hi + 4);
;         float xv[8]; unpack8(xr, xv);
; #pragma unroll
;         for (int e = 0; e < 4; ++e) { xv[e] *= w0[e]; xv[4 + e] *= w1[e]; }
;         st = __builtin_amdgcn_mfma_f32_32x32x16_bf16(*(const LAS bf16x8*)(btrow + ks * 32), pack8f(xv), st, 0, 0, 0); }
; }
.LBB0_420:
	s_waitcnt lgkmcnt(0)
	s_barrier
	ds_write_b128 v235, v[72:75]
	ds_write_b128 v235, v[88:91] offset:8704
	ds_write_b128 v235, v[84:87] offset:17408
	ds_write_b128 v235, v[92:95] offset:26112
	v_cndmask_b32_e64 v2, 0, 1, s[60:61]
	s_mov_b64 s[38:39], -1
	s_and_b64 vcc, exec, s[58:59]
	v_cmp_ne_u32_e64 s[40:41], 1, v2
	s_cbranch_vccz .LBB0_424
	s_nop 6
	v_mov_b64_e32 v[4:5], v[20:21]
	s_and_b64 vcc, exec, s[40:41]
	v_mov_b64_e32 v[6:7], v[22:23]
	v_mov_b64_e32 v[8:9], v[24:25]
	v_mov_b64_e32 v[10:11], v[26:27]
	v_mov_b64_e32 v[12:13], v[28:29]
	v_mov_b64_e32 v[14:15], v[30:31]
	v_mov_b64_e32 v[16:17], v[32:33]
	v_mov_b64_e32 v[18:19], v[34:35]
	s_cbranch_vccnz .LBB0_423
	v_mov_b32_e32 v2, s0
	ds_read_b32 v2, v2
	v_add_u32_e32 v112, 0, v221
	v_add_u32_e32 v120, 0x13a00, v112
	s_waitcnt lgkmcnt(0)
	v_pk_mul_f32 v[18:19], v[34:35], v[2:3] op_sel_hi:[1,0]
	v_pk_mul_f32 v[16:17], v[32:33], v[2:3] op_sel_hi:[1,0]
	v_pk_mul_f32 v[14:15], v[30:31], v[2:3] op_sel_hi:[1,0]
	v_pk_mul_f32 v[12:13], v[28:29], v[2:3] op_sel_hi:[1,0]
	v_pk_mul_f32 v[10:11], v[26:27], v[2:3] op_sel_hi:[1,0]
	v_pk_mul_f32 v[8:9], v[24:25], v[2:3] op_sel_hi:[1,0]
	v_pk_mul_f32 v[6:7], v[22:23], v[2:3] op_sel_hi:[1,0]
	v_pk_mul_f32 v[4:5], v[20:21], v[2:3] op_sel_hi:[1,0]
	v_add_u32_e32 v2, v231, v219
	ds_read_b128 v[108:111], v2 offset:53248
	ds_read_b128 v[112:115], v120
	ds_read_b128 v[116:119], v120 offset:16
	s_waitcnt lgkmcnt(2)
	v_lshlrev_b32_e32 v121, 16, v108
	v_and_b32_e32 v108, 0xffff0000, v108
	v_lshlrev_b32_e32 v122, 16, v109
	v_and_b32_e32 v109, 0xffff0000, v109
	v_lshlrev_b32_e32 v123, 16, v110
	v_and_b32_e32 v110, 0xffff0000, v110
	v_lshlrev_b32_e32 v124, 16, v111
	v_and_b32_e32 v111, 0xffff0000, v111
	s_waitcnt lgkmcnt(1)
	v_mul_f32_e32 v112, v112, v121
	v_add_u32_e32 v121, v218, v219
	v_mul_f32_e32 v113, v113, v108
	s_waitcnt lgkmcnt(0)
	v_mul_f32_e32 v117, v117, v110
	v_mul_f32_e32 v115, v115, v109
	v_mul_f32_e32 v119, v119, v111
	ds_read_b128 v[108:111], v121 offset:34816
	v_mul_f32_e32 v114, v114, v122
	v_mul_f32_e32 v116, v116, v123
	v_mul_f32_e32 v118, v118, v124
	v_cvt_pk_bf16_f32 v112, v112, v113
	v_cvt_pk_bf16_f32 v113, v114, v115
	v_cvt_pk_bf16_f32 v114, v116, v117
	v_cvt_pk_bf16_f32 v115, v118, v119
	s_waitcnt lgkmcnt(0)
	v_mfma_f32_32x32x16_bf16 v[4:19], v[108:111], v[112:115], v[4:19]
	ds_read_b128 v[108:111], v2 offset:53280
	ds_read_b128 v[112:115], v120 offset:64
	ds_read_b128 v[116:119], v120 offset:80
	s_waitcnt lgkmcnt(2)
	v_lshlrev_b32_e32 v122, 16, v108
	v_and_b32_e32 v108, 0xffff0000, v108
	v_lshlrev_b32_e32 v123, 16, v109
	v_and_b32_e32 v109, 0xffff0000, v109
	v_lshlrev_b32_e32 v124, 16, v110
	v_and_b32_e32 v110, 0xffff0000, v110
	v_lshlrev_b32_e32 v125, 16, v111
	v_and_b32_e32 v111, 0xffff0000, v111
	s_waitcnt lgkmcnt(1)
	v_mul_f32_e32 v113, v113, v108
	s_waitcnt lgkmcnt(0)
	v_mul_f32_e32 v117, v117, v110
	v_mul_f32_e32 v115, v115, v109
	v_mul_f32_e32 v119, v119, v111
	ds_read_b128 v[108:111], v121 offset:34848
	v_mul_f32_e32 v112, v112, v122
	v_mul_f32_e32 v114, v114, v123
	v_mul_f32_e32 v116, v116, v124
	v_mul_f32_e32 v118, v118, v125
	v_cvt_pk_bf16_f32 v112, v112, v113
	v_cvt_pk_bf16_f32 v113, v114, v115
	v_cvt_pk_bf16_f32 v114, v116, v117
	v_cvt_pk_bf16_f32 v115, v118, v119
	s_waitcnt lgkmcnt(0)
	v_mfma_f32_32x32x16_bf16 v[4:19], v[108:111], v[112:115], v[4:19]
	ds_read_b128 v[108:111], v2 offset:53312
	ds_read_b128 v[112:115], v120 offset:128
	ds_read_b128 v[116:119], v120 offset:144
	s_waitcnt lgkmcnt(2)
	v_lshlrev_b32_e32 v122, 16, v108
	v_and_b32_e32 v108, 0xffff0000, v108
	v_lshlrev_b32_e32 v123, 16, v109
	v_and_b32_e32 v109, 0xffff0000, v109
	v_lshlrev_b32_e32 v124, 16, v110
	v_and_b32_e32 v110, 0xffff0000, v110
	v_lshlrev_b32_e32 v125, 16, v111
	v_and_b32_e32 v111, 0xffff0000, v111
	s_waitcnt lgkmcnt(1)
	v_mul_f32_e32 v113, v113, v108
	s_waitcnt lgkmcnt(0)
	v_mul_f32_e32 v117, v117, v110
	v_mul_f32_e32 v115, v115, v109
	v_mul_f32_e32 v119, v119, v111
	ds_read_b128 v[108:111], v121 offset:34880
	v_mul_f32_e32 v112, v112, v122
	v_mul_f32_e32 v114, v114, v123
	v_mul_f32_e32 v116, v116, v124
	v_mul_f32_e32 v118, v118, v125
	v_cvt_pk_bf16_f32 v112, v112, v113
	v_cvt_pk_bf16_f32 v113, v114, v115
	v_cvt_pk_bf16_f32 v114, v116, v117
	v_cvt_pk_bf16_f32 v115, v118, v119
	s_waitcnt lgkmcnt(0)
	v_mfma_f32_32x32x16_bf16 v[4:19], v[108:111], v[112:115], v[4:19]
	ds_read_b128 v[108:111], v2 offset:53344
	ds_read_b128 v[112:115], v120 offset:192
	ds_read_b128 v[116:119], v120 offset:208
	s_waitcnt lgkmcnt(2)
	v_lshlrev_b32_e32 v2, 16, v108
	v_and_b32_e32 v108, 0xffff0000, v108
	v_lshlrev_b32_e32 v120, 16, v109
	v_and_b32_e32 v109, 0xffff0000, v109
	v_lshlrev_b32_e32 v122, 16, v110
	v_and_b32_e32 v110, 0xffff0000, v110
	v_lshlrev_b32_e32 v123, 16, v111
	v_and_b32_e32 v111, 0xffff0000, v111
	s_waitcnt lgkmcnt(1)
	v_mul_f32_e32 v2, v112, v2
	v_mul_f32_e32 v112, v113, v108
	s_waitcnt lgkmcnt(0)
	v_mul_f32_e32 v117, v117, v110
	v_mul_f32_e32 v113, v114, v120
	v_mul_f32_e32 v114, v115, v109
	v_mul_f32_e32 v115, v119, v111
	ds_read_b128 v[108:111], v121 offset:34912
	v_mul_f32_e32 v116, v116, v122
	v_mul_f32_e32 v118, v118, v123
	v_cvt_pk_bf16_f32 v112, v2, v112
	v_cvt_pk_bf16_f32 v113, v113, v114
	v_cvt_pk_bf16_f32 v114, v116, v117
	v_cvt_pk_bf16_f32 v115, v118, v115
	s_waitcnt lgkmcnt(0)
	v_mfma_f32_32x32x16_bf16 v[4:19], v[108:111], v[112:115], v[4:19]

; #define LAS __attribute__((address_space(3)))
; __device__ __forceinline__ void phase(lptr lds, const bf16* Z, const bf16* XACT, const bf16* BCT, const float* DTV, const float* a_log, const float* dskip, bf16* AM, float* SSQ, int G, int bx) {
;     ...
;             if (wid == 7) { LAS float* vw = (LAS float*)(lds + O_VEC); vw[V_DT / 4 + lane] = P.sv[0]; vw[V_ACS / 4 + lane] = P.sv[1]; vw[V_W / 4 + lane] = P.sv[2]; vw[V_E / 4 + lane] = P.sv[3]; }
.LBB0_430:
	s_waitcnt lgkmcnt(0)
	s_barrier
	s_andn2_b64 vcc, exec, s[56:57]
	ds_write_b128 v236, v[96:99] offset:34816
	ds_write_b128 v236, v[100:103] offset:44032
	ds_write_b128 v236, v[104:107] offset:53248
	s_cbranch_vccnz .LBB0_432
	ds_write2st64_b32 v217, v247, v248 offset1:1
	ds_write2st64_b32 v217, v249, v250 offset0:2 offset1:3

; #define LAS __attribute__((address_space(3)))
; __device__ __forceinline__ void unpack8(const u32x4 w, float (&v)[8]) { v[0] = bf_lo(w.x); v[1] = bf_hi(w.x); v[2] = bf_lo(w.y); v[3] = bf_hi(w.y); v[4] = bf_lo(w.z); v[5] = bf_hi(w.z); v[6] = bf_lo(w.w); v[7] = bf_hi(w.w); }
; __device__ __forceinline__ bf16x8 pack8f(const float (&v)[8]) { u32x4 w = {cvt_pk_bf16(v[0], v[1]), cvt_pk_bf16(v[2], v[3]), cvt_pk_bf16(v[4], v[5]), cvt_pk_bf16(v[6], v[7])}; return *reinterpret_cast<bf16x8*>(&w); }
; __device__ __forceinline__ void state_update(f32x16& st, lptr lds, const LAS float* vec, int wid, int r32, int hi) {
;     const int nt = wid & 3, pt = wid >> 2; const float cdec = vec[V_E / 4 + 63];
; #pragma unroll
;     for (int r = 0; r < 16; ++r) st[r] *= cdec;
;     const lptr btrow = lds + O_BT + (32 * nt + r32) * PBT + hi * 16; const lptr xtrow = lds + O_XT + (32 * pt + r32) * PXT + hi * 16;
; #pragma unroll
;     for (int ks = 0; ks < 4; ++ks) { const u32x4 xr = *(const LAS u32x4*)(xtrow + ks * 32);
;         const f32x4 w0 = *(const LAS f32x4*)(vec + V_W / 4 + 16 * ks + 8 * hi), w1 = *(const LAS f32x4*)(vec + V_W / 4 + 16 * ks + 8 * hi + 4);
;         float xv[8]; unpack8(xr, xv);
; #pragma unroll
;         for (int e = 0; e < 4; ++e) { xv[e] *= w0[e]; xv[4 + e] *= w1[e]; }
;         st = __builtin_amdgcn_mfma_f32_32x32x16_bf16(*(const LAS bf16x8*)(btrow + ks * 32), pack8f(xv), st, 0, 0, 0); }
; }
; __device__ __forceinline__ void phase(lptr lds, const bf16* Z, const bf16* XACT, const bf16* BCT, const float* DTV, const float* a_log, const float* dskip, bf16* AM, float* SSQ, int G, int bx) {
;     ...
;               loads(P, XSh, BCg, SVh, cn, tid, lane);
.LBB0_440:
	s_waitcnt lgkmcnt(0)
	s_barrier
	s_waitcnt vmcnt(26)
	ds_write_b128 v235, v[52:55]
	ds_write_b128 v235, v[56:59] offset:8704
	ds_write_b128 v235, v[64:67] offset:17408
	ds_write_b128 v235, v[60:63] offset:26112
	s_and_b64 vcc, exec, s[42:43]
	s_mov_b64 s[42:43], -1
	s_cbranch_vccnz .LBB0_444
	v_mov_b64_e32 v[4:5], v[20:21]
	s_and_b64 vcc, exec, s[40:41]
	v_mov_b64_e32 v[6:7], v[22:23]
	v_mov_b64_e32 v[8:9], v[24:25]
	v_mov_b64_e32 v[10:11], v[26:27]
	v_mov_b64_e32 v[12:13], v[28:29]
	v_mov_b64_e32 v[14:15], v[30:31]
	v_mov_b64_e32 v[16:17], v[32:33]
	v_mov_b64_e32 v[18:19], v[34:35]
	s_cbranch_vccnz .LBB0_443
	v_mov_b32_e32 v2, s0
	ds_read_b32 v2, v2
	v_add_u32_e32 v112, 0, v221
	v_add_u32_e32 v120, 0x13a00, v112
	s_waitcnt lgkmcnt(0)
	v_pk_mul_f32 v[18:19], v[34:35], v[2:3] op_sel_hi:[1,0]
	v_pk_mul_f32 v[16:17], v[32:33], v[2:3] op_sel_hi:[1,0]
	v_pk_mul_f32 v[14:15], v[30:31], v[2:3] op_sel_hi:[1,0]
	v_pk_mul_f32 v[12:13], v[28:29], v[2:3] op_sel_hi:[1,0]
	v_pk_mul_f32 v[10:11], v[26:27], v[2:3] op_sel_hi:[1,0]
	v_pk_mul_f32 v[8:9], v[24:25], v[2:3] op_sel_hi:[1,0]
	v_pk_mul_f32 v[6:7], v[22:23], v[2:3] op_sel_hi:[1,0]
	v_pk_mul_f32 v[4:5], v[20:21], v[2:3] op_sel_hi:[1,0]
	v_add_u32_e32 v2, v231, v219
	ds_read_b128 v[108:111], v2 offset:53248
	ds_read_b128 v[112:115], v120
	ds_read_b128 v[116:119], v120 offset:16
	s_waitcnt lgkmcnt(2)
	v_lshlrev_b32_e32 v121, 16, v108
	v_and_b32_e32 v108, 0xffff0000, v108
	v_lshlrev_b32_e32 v122, 16, v109
	v_and_b32_e32 v109, 0xffff0000, v109
	v_lshlrev_b32_e32 v123, 16, v110
	v_and_b32_e32 v110, 0xffff0000, v110
	v_lshlrev_b32_e32 v124, 16, v111
	v_and_b32_e32 v111, 0xffff0000, v111
	s_waitcnt lgkmcnt(1)
	v_mul_f32_e32 v112, v112, v121
	v_add_u32_e32 v121, v218, v219
	v_mul_f32_e32 v113, v113, v108
	s_waitcnt lgkmcnt(0)
	v_mul_f32_e32 v117, v117, v110
	v_mul_f32_e32 v115, v115, v109
	v_mul_f32_e32 v119, v119, v111
	ds_read_b128 v[108:111], v121 offset:34816
	v_mul_f32_e32 v114, v114, v122
	v_mul_f32_e32 v116, v116, v123
	v_mul_f32_e32 v118, v118, v124
	v_cvt_pk_bf16_f32 v112, v112, v113
	v_cvt_pk_bf16_f32 v113, v114, v115
	v_cvt_pk_bf16_f32 v114, v116, v117
	v_cvt_pk_bf16_f32 v115, v118, v119
	s_waitcnt lgkmcnt(0)
	v_mfma_f32_32x32x16_bf16 v[4:19], v[108:111], v[112:115], v[4:19]
	ds_read_b128 v[108:111], v2 offset:53280
	ds_read_b128 v[112:115], v120 offset:64
	ds_read_b128 v[116:119], v120 offset:80
	s_waitcnt lgkmcnt(2)
	v_lshlrev_b32_e32 v122, 16, v108
	v_and_b32_e32 v108, 0xffff0000, v108
	v_lshlrev_b32_e32 v123, 16, v109
	v_and_b32_e32 v109, 0xffff0000, v109
	v_lshlrev_b32_e32 v124, 16, v110
	v_and_b32_e32 v110, 0xffff0000, v110
	v_lshlrev_b32_e32 v125, 16, v111
	v_and_b32_e32 v111, 0xffff0000, v111
	s_waitcnt lgkmcnt(1)
	v_mul_f32_e32 v113, v113, v108
	s_waitcnt lgkmcnt(0)
	v_mul_f32_e32 v117, v117, v110
	v_mul_f32_e32 v115, v115, v109
	v_mul_f32_e32 v119, v119, v111
	ds_read_b128 v[108:111], v121 offset:34848
	v_mul_f32_e32 v112, v112, v122
	v_mul_f32_e32 v114, v114, v123
	v_mul_f32_e32 v116, v116, v124
	v_mul_f32_e32 v118, v118, v125
	v_cvt_pk_bf16_f32 v112, v112, v113
	v_cvt_pk_bf16_f32 v113, v114, v115
	v_cvt_pk_bf16_f32 v114, v116, v117
	v_cvt_pk_bf16_f32 v115, v118, v119
	s_waitcnt lgkmcnt(0)
	v_mfma_f32_32x32x16_bf16 v[4:19], v[108:111], v[112:115], v[4:19]
	ds_read_b128 v[108:111], v2 offset:53312
	ds_read_b128 v[112:115], v120 offset:128
	ds_read_b128 v[116:119], v120 offset:144
	s_waitcnt lgkmcnt(2)
	v_lshlrev_b32_e32 v122, 16, v108
	v_and_b32_e32 v108, 0xffff0000, v108
	v_lshlrev_b32_e32 v123, 16, v109
	v_and_b32_e32 v109, 0xffff0000, v109
	v_lshlrev_b32_e32 v124, 16, v110
	v_and_b32_e32 v110, 0xffff0000, v110
	v_lshlrev_b32_e32 v125, 16, v111
	v_and_b32_e32 v111, 0xffff0000, v111
	s_waitcnt lgkmcnt(1)
	v_mul_f32_e32 v113, v113, v108
	s_waitcnt lgkmcnt(0)
	v_mul_f32_e32 v117, v117, v110
	v_mul_f32_e32 v115, v115, v109
	v_mul_f32_e32 v119, v119, v111
	ds_read_b128 v[108:111], v121 offset:34880
	v_mul_f32_e32 v112, v112, v122
	v_mul_f32_e32 v114, v114, v123
	v_mul_f32_e32 v116, v116, v124
	v_mul_f32_e32 v118, v118, v125
	v_cvt_pk_bf16_f32 v112, v112, v113
	v_cvt_pk_bf16_f32 v113, v114, v115
	v_cvt_pk_bf16_f32 v114, v116, v117
	v_cvt_pk_bf16_f32 v115, v118, v119
	s_waitcnt lgkmcnt(0)
	v_mfma_f32_32x32x16_bf16 v[4:19], v[108:111], v[112:115], v[4:19]
	ds_read_b128 v[108:111], v2 offset:53344
	ds_read_b128 v[112:115], v120 offset:192
	ds_read_b128 v[116:119], v120 offset:208
	s_waitcnt lgkmcnt(2)
	v_lshlrev_b32_e32 v2, 16, v108
	v_and_b32_e32 v108, 0xffff0000, v108
	v_lshlrev_b32_e32 v120, 16, v109
	v_and_b32_e32 v109, 0xffff0000, v109
	v_lshlrev_b32_e32 v122, 16, v110
	v_and_b32_e32 v110, 0xffff0000, v110
	v_lshlrev_b32_e32 v123, 16, v111
	v_and_b32_e32 v111, 0xffff0000, v111
	s_waitcnt lgkmcnt(1)
	v_mul_f32_e32 v2, v112, v2
	v_mul_f32_e32 v112, v113, v108
	s_waitcnt lgkmcnt(0)
	v_mul_f32_e32 v117, v117, v110
	v_mul_f32_e32 v113, v114, v120
	v_mul_f32_e32 v114, v115, v109
	v_mul_f32_e32 v115, v119, v111
	ds_read_b128 v[108:111], v121 offset:34912
	v_mul_f32_e32 v116, v116, v122
	v_mul_f32_e32 v118, v118, v123
	v_cvt_pk_bf16_f32 v112, v2, v112
	v_cvt_pk_bf16_f32 v113, v113, v114
	v_cvt_pk_bf16_f32 v114, v116, v117
	v_cvt_pk_bf16_f32 v115, v118, v115
	s_waitcnt lgkmcnt(0)
	v_mfma_f32_32x32x16_bf16 v[4:19], v[108:111], v[112:115], v[4:19]

; #define SBAR() __builtin_amdgcn_sched_barrier(0)
; #define VMW() asm volatile("s_waitcnt vmcnt(0)" ::: "memory")
; #define SLOAD_H(Kp, Vp, k0) do { S.st_v0 = ld8((const bf16*)ROWB(Vp, k0, 0)); S.st_v1 = ld8((const bf16*)ROWB(Vp, k0, 1)); S.st_k0 = ld8((const bf16*)ROWB(Kp, k0, 0)); S.st_k1 = ld8((const bf16*)ROWB(Kp, k0, 1)); } while (0)
; #define SWRITE_HV(bf) do { *(LAS bf16x8*)(V_lds + (bf) * SHM_V + vst0) = S.st_v0; *(LAS bf16x8*)(V_lds + (bf) * SHM_V + vst1) = S.st_v1; } while (0)
; #define SWRITE_H(bf) do { SWRITE_HV(bf); SWRITE_HK(bf); } while (0)
; #define MASKT(P0_, P1_, t) do { const int kb_ = KBASE(t); if (kb_ + KVBLK - 1 > qlo) mask_tile(P0_, P1_, qm - kb_); } while (0)
; __device__ __forceinline__ void partialSM(f32x16& p0, f32x16& p1, float& m_reg, float& mn, float& alpha) {
;     float pmax = p0[0];
; #pragma unroll
;     for (int r = 1; r < 16; ++r) pmax = fmaxf(pmax, p0[r]);
; #pragma unroll
;     for (int r = 0; r < 16; ++r) pmax = fmaxf(pmax, p1[r]);
;     { auto rr = __builtin_amdgcn_permlane32_swap(__float_as_uint(pmax), __float_as_uint(pmax), false, false); pmax = fmaxf(__uint_as_float(rr[0]), __uint_as_float(rr[1])); }
;     constexpr float C2 = 1.4426950408889634f * SCALE;
;     if (__builtin_expect(__all((pmax - m_reg) * SCALE <= THR), 1)) { mn = m_reg; alpha = 1.f; }
;     else { mn = fmaxf(m_reg, pmax); alpha = __builtin_amdgcn_exp2f((m_reg - mn) * C2); m_reg = mn; }
;     const float mnL = -mn * C2;
; #pragma unroll
;     for (int r = 0; r < 16; ++r) p0[r] = fmaf(p0[r], C2, mnL);
; #pragma unroll
;     for (int r = 0; r < 16; ++r) p1[r] = fmaf(p1[r], C2, mnL);
; #pragma unroll
;     for (int r = 0; r < 16; ++r) p0[r] = __builtin_amdgcn_exp2f(p0[r]);
; }
; __device__ __forceinline__ void block(const BlockRef& cur, const BlockRef& nxt, lptr lds, Seam& S) {
;     ...
;     f32x16 pA0, pA1, pB0, pB1; float mnA, mnB, alA, alB; bf16x8 pa0, pa1, pa2, pa3;
;     SWRITE_HV(0); SBAR();
;     if (NT > 1) SLOAD_H(Kh, Vh, KBASE(1));
;     SBAR(); qkt<0>(pA0, pA1, K_lds, r32, hi, S.qr, bl + KBASE(0));
;     MASKT(pA0, pA1, 0); partialSM(pA0, pA1, m_reg, mnA, alA);
;     if (NT > 1) { VMW(); SWRITE_H(1); }
;     __syncthreads();
.LBB0_526:
	s_nop 7
	v_max_f32_e32 v50, v19, v19
	v_max_f32_e32 v51, v18, v18
	v_max_f32_e32 v50, v51, v50
	v_max3_f32 v50, v50, v20, v21
	v_max3_f32 v50, v50, v22, v23
	v_max3_f32 v50, v50, v24, v25
	v_max3_f32 v50, v50, v26, v27
	v_max3_f32 v50, v50, v28, v29
	v_max3_f32 v50, v50, v30, v31
	v_max3_f32 v50, v50, v32, v33
	v_max3_f32 v50, v50, v2, v3
	v_max3_f32 v50, v50, v4, v5
	v_max3_f32 v50, v50, v6, v7
	v_max3_f32 v50, v50, v8, v9
	v_max3_f32 v50, v50, v10, v11
	v_max3_f32 v50, v50, v12, v13
	v_max3_f32 v50, v50, v14, v15
	v_max3_f32 v50, v50, v16, v17
	v_mov_b32_e32 v51, v50
	s_nop 1
	v_permlane32_swap_b32_e32 v50, v51
	v_max_f32_e32 v51, v51, v51
	v_max_f32_e32 v50, v50, v50
	s_add_i32 s7, s87, 0x100
	v_max_f32_e32 v50, v50, v51
	s_lshr_b32 s95, s7, 6
	s_and_b32 s7, s6, 0x3fffffc0
	v_add_f32_e32 v51, 0x7149f2ca, v50
	s_lshl_b32 s7, s7, 2
	v_mul_f32_e32 v51, 0x3db504f3, v51
	v_max_f32_e32 v50, 0xf149f2ca, v50
	s_add_i32 s7, s7, 0
	v_cmp_ge_f32_e32 vcc, s93, v51
	v_sub_f32_e32 v51, 0xf149f2ca, v50
	s_add_i32 s8, s7, 0x10000
	v_mul_f32_e32 v51, 0x3e0293ee, v51
	v_exp_f32_e32 v51, v51
	s_cmp_eq_u64 vcc, exec
	s_cselect_b64 vcc, -1, 0
	v_cndmask_b32_e32 v229, v50, v223, vcc
	v_mul_f32_e32 v50, 0xbe0293ee, v229
	v_cndmask_b32_e64 v204, v51, 1.0, vcc
	v_mov_b32_e32 v51, v50
	v_fmamk_f32 v18, v18, 0x3e0293ee, v50
	v_fmamk_f32 v19, v19, 0x3e0293ee, v50
	v_fmamk_f32 v20, v20, 0x3e0293ee, v50
	v_fmamk_f32 v21, v21, 0x3e0293ee, v50
	v_fmamk_f32 v22, v22, 0x3e0293ee, v50
	v_fmamk_f32 v23, v23, 0x3e0293ee, v50
	v_fmamk_f32 v24, v24, 0x3e0293ee, v50
	v_fmamk_f32 v25, v25, 0x3e0293ee, v50
	v_fmamk_f32 v26, v26, 0x3e0293ee, v50
	v_fmamk_f32 v27, v27, 0x3e0293ee, v50
	v_fmamk_f32 v28, v28, 0x3e0293ee, v50
	v_fmamk_f32 v29, v29, 0x3e0293ee, v50
	v_fmamk_f32 v30, v30, 0x3e0293ee, v50
	v_fmamk_f32 v31, v31, 0x3e0293ee, v50
	v_fmamk_f32 v32, v32, 0x3e0293ee, v50
	v_fmac_f32_e32 v51, 0x3e0293ee, v33
	v_exp_f32_e32 v98, v18
	v_exp_f32_e32 v99, v19
	v_exp_f32_e32 v100, v20
	v_exp_f32_e32 v101, v21
	v_exp_f32_e32 v102, v22
	v_exp_f32_e32 v103, v23
	v_exp_f32_e32 v104, v24
	v_exp_f32_e32 v105, v25
	v_exp_f32_e32 v106, v26
	v_exp_f32_e32 v107, v27
	v_exp_f32_e32 v108, v28
	v_exp_f32_e32 v109, v29
	v_exp_f32_e32 v110, v30
	v_exp_f32_e32 v111, v31
	v_exp_f32_e32 v112, v32
	v_exp_f32_e32 v113, v51
	s_waitcnt vmcnt(0)
	s_waitcnt vmcnt(3)
	ds_write_b128 v216, v[34:37] offset:16384
	s_waitcnt vmcnt(2)
	ds_write_b128 v217, v[38:41] offset:16384
	s_waitcnt vmcnt(1)
	ds_write_b128 v224, v[42:45] offset:49152
	s_waitcnt vmcnt(0)
	ds_write_b128 v224, v[46:49] offset:57344
	v_mov_b32_e32 v34, v195
	v_mov_b32_e32 v35, v195
	v_mov_b32_e32 v48, v195
	v_mov_b32_e32 v49, v195
	v_pk_fma_f32 v[128:129], v[16:17], s[94:95], v[50:51] op_sel_hi:[1,0,0]
	v_pk_fma_f32 v[126:127], v[14:15], s[94:95], v[50:51] op_sel_hi:[1,0,0]
	v_pk_fma_f32 v[124:125], v[12:13], s[94:95], v[50:51] op_sel_hi:[1,0,0]
	v_pk_fma_f32 v[122:123], v[10:11], s[94:95], v[50:51] op_sel_hi:[1,0,0]
	v_pk_fma_f32 v[120:121], v[8:9], s[94:95], v[50:51] op_sel_hi:[1,0,0]
	v_pk_fma_f32 v[118:119], v[6:7], s[94:95], v[50:51] op_sel_hi:[1,0,0]
	v_pk_fma_f32 v[116:117], v[4:5], s[94:95], v[50:51] op_sel_hi:[1,0,0]
	v_pk_fma_f32 v[114:115], v[2:3], s[94:95], v[50:51] op_sel_hi:[1,0,0]
	v_mov_b32_e32 v36, v195
	v_mov_b32_e32 v37, v195
	v_mov_b32_e32 v38, v195
	v_mov_b32_e32 v39, v195
	v_mov_b32_e32 v40, v195
	v_mov_b32_e32 v41, v195
	v_mov_b32_e32 v42, v195
	v_mov_b32_e32 v43, v195
	v_mov_b32_e32 v44, v195
	v_mov_b32_e32 v45, v195
	v_mov_b32_e32 v46, v195
	v_mov_b32_e32 v47, v195
	v_mov_b64_e32 v[64:65], v[48:49]
	v_mov_b64_e32 v[18:19], v[34:35]
	v_mov_b64_e32 v[2:3], v[34:35]
	v_mov_b64_e32 v[96:97], v[48:49]
	s_mov_b32 s6, 2
	s_or_b32 s7, s90, 31
	v_lshl_add_u32 v227, v196, 2, s8
	v_lshl_add_u32 v225, v208, 2, s8
	v_add_u32_e32 v231, s90, v213
	v_mov_b32_e32 v230, 0
	s_movk_i32 s88, 0xbf
	v_mov_b32_e32 v232, v214
	v_mov_b64_e32 v[62:63], v[46:47]
	v_mov_b64_e32 v[60:61], v[44:45]
	v_mov_b64_e32 v[58:59], v[42:43]
	v_mov_b64_e32 v[56:57], v[40:41]
	v_mov_b64_e32 v[54:55], v[38:39]
	v_mov_b64_e32 v[52:53], v[36:37]
	v_mov_b64_e32 v[50:51], v[34:35]
	v_mov_b64_e32 v[20:21], v[36:37]
	v_mov_b64_e32 v[22:23], v[38:39]
	v_mov_b64_e32 v[24:25], v[40:41]
	v_mov_b64_e32 v[26:27], v[42:43]
	v_mov_b64_e32 v[28:29], v[44:45]
	v_mov_b64_e32 v[30:31], v[46:47]
	v_mov_b64_e32 v[32:33], v[48:49]
	v_mov_b64_e32 v[4:5], v[36:37]
	v_mov_b64_e32 v[6:7], v[38:39]
	v_mov_b64_e32 v[8:9], v[40:41]
	v_mov_b64_e32 v[10:11], v[42:43]
	v_mov_b64_e32 v[12:13], v[44:45]
	v_mov_b64_e32 v[14:15], v[46:47]
	v_mov_b64_e32 v[16:17], v[48:49]
	v_mov_b64_e32 v[94:95], v[46:47]
	v_mov_b64_e32 v[92:93], v[44:45]
	v_mov_b64_e32 v[90:91], v[42:43]
	v_mov_b64_e32 v[88:89], v[40:41]
	v_mov_b64_e32 v[86:87], v[38:39]
	v_mov_b64_e32 v[84:85], v[36:37]
	v_mov_b64_e32 v[82:83], v[34:35]
	s_waitcnt lgkmcnt(0)
	s_barrier
	v_readfirstlane_b32 s32, v0
	s_branch .LBB0_529

; #define LAS __attribute__((address_space(3)))
; template <int KB>
; __device__ __forceinline__ void qkt(f32x16& p0, f32x16& p1, lptr K_lds, int r32, int hi, const bf16x8* qr, const LAS float* blk) {
;     { const LAS f32x4* bp = (const LAS f32x4*)blk;
;       const f32x4 a0 = bp[0], a1 = bp[2], a2 = bp[4], a3 = bp[6], c0 = bp[8], c1 = bp[10], c2 = bp[12], c3 = bp[14];
;       p0 = (f32x16){a0[0], a0[1], a0[2], a0[3], a1[0], a1[1], a1[2], a1[3], a2[0], a2[1], a2[2], a2[3], a3[0], a3[1], a3[2], a3[3]};
;       p1 = (f32x16){c0[0], c0[1], c0[2], c0[3], c1[0], c1[1], c1[2], c1[3], c2[0], c2[1], c2[2], c2[3], c3[0], c3[1], c3[2], c3[3]}; }
;     lptr kb[4];
; #pragma unroll
;     for (int dd = 0; dd < 4; ++dd) kb[dd] = K_lds + KB * SHM_K + KSWZ(r32, (dd * 16 + hi * 8) * 2);
; #pragma unroll
;     for (int d0 = 0; d0 < 8; ++d0) { lptr a = kb[d0 & 3] + (d0 >> 2) * 128;
;         bf16x8 b0 = *(const LAS bf16x8*)(a);
;         bf16x8 b1 = *(const LAS bf16x8*)(a + 32 * 256);
;         p0 = __builtin_amdgcn_mfma_f32_32x32x16_bf16(b0, qr[d0], p0, 0, 0, 0);
;         p1 = __builtin_amdgcn_mfma_f32_32x32x16_bf16(b1, qr[d0], p1, 0, 0, 0); }
; }
.LBB0_529:
	s_add_u32 s12, s84, 0x8000
	s_addc_u32 s13, s85, 0
	s_add_u32 s14, s84, 0xa000
	s_addc_u32 s15, s85, 0
	s_add_u32 s16, s82, 0x8000
	s_addc_u32 s17, s83, 0
	s_add_u32 s18, s82, 0xa000
	s_addc_u32 s19, s83, 0
	v_lshl_add_u64 v[178:179], s[12:13], 0, v[198:199]
	v_lshl_add_u64 v[182:183], s[14:15], 0, v[198:199]
	v_lshl_add_u64 v[186:187], s[16:17], 0, v[198:199]
	v_lshl_add_u64 v[190:191], s[18:19], 0, v[198:199]
	global_load_dwordx4 v[178:181], v[178:179], off
	global_load_dwordx4 v[182:185], v[182:183], off
	global_load_dwordx4 v[186:189], v[186:187], off
	global_load_dwordx4 v[190:193], v[190:191], off
	s_add_i32 s8, s88, 0xffffff81
	s_cmp_le_u32 s8, s7
	s_cselect_b64 s[10:11], -1, 0
	s_cmp_gt_u32 s8, s7
	s_cbranch_scc1 .Latta_531
	ds_read_b128 v[66:69], v232
	ds_read_b128 v[70:73], v232 offset:32
	ds_read_b128 v[74:77], v232 offset:64
	ds_read_b128 v[78:81], v232 offset:96
	ds_read_b128 v[162:165], v218 offset:49152
	ds_read_b128 v[166:169], v218 offset:57344
	ds_read_b128 v[82:85], v232 offset:128
	ds_read_b128 v[86:89], v232 offset:160
	ds_read_b128 v[90:93], v232 offset:192
	ds_read_b128 v[94:97], v232 offset:224
	ds_read_b128 v[170:173], v219 offset:49152
	ds_read_b128 v[174:177], v219 offset:57344
	ds_read_b128 v[234:237], v220 offset:49152
	ds_read_b128 v[238:241], v220 offset:57344
	ds_read_b128 v[246:249], v221 offset:49152
	s_waitcnt lgkmcnt(10)
	v_mfma_f32_32x32x16_bf16 v[66:81], v[162:165], v[158:161], v[66:81]
	ds_read_b128 v[250:253], v221 offset:57344
	s_waitcnt lgkmcnt(6)
	v_mfma_f32_32x32x16_bf16 v[82:97], v[166:169], v[158:161], v[82:97]
	ds_read_b128 v[162:165], v218 offset:49280
	s_waitcnt lgkmcnt(6)
	v_mfma_f32_32x32x16_bf16 v[66:81], v[170:173], v[154:157], v[66:81]
	ds_read_b128 v[166:169], v218 offset:57472
	s_waitcnt lgkmcnt(6)
	v_mfma_f32_32x32x16_bf16 v[82:97], v[174:177], v[154:157], v[82:97]
	ds_read_b128 v[170:173], v219 offset:49280
	s_waitcnt lgkmcnt(6)
	v_mfma_f32_32x32x16_bf16 v[66:81], v[234:237], v[150:153], v[66:81]
	ds_read_b128 v[174:177], v219 offset:57472
	s_waitcnt lgkmcnt(6)
	v_mfma_f32_32x32x16_bf16 v[82:97], v[238:241], v[150:153], v[82:97]
	ds_read_b128 v[234:237], v220 offset:49280
	s_waitcnt lgkmcnt(6)
	v_mfma_f32_32x32x16_bf16 v[66:81], v[246:249], v[146:149], v[66:81]
	ds_read_b128 v[238:241], v220 offset:57472
	s_waitcnt lgkmcnt(6)
	v_mfma_f32_32x32x16_bf16 v[82:97], v[250:253], v[146:149], v[82:97]
	ds_read_b128 v[246:249], v221 offset:49280
	s_waitcnt lgkmcnt(6)
	v_mfma_f32_32x32x16_bf16 v[66:81], v[162:165], v[142:145], v[66:81]
	ds_read_b128 v[250:253], v221 offset:57472
	s_waitcnt lgkmcnt(6)
	v_mfma_f32_32x32x16_bf16 v[82:97], v[166:169], v[142:145], v[82:97]
	s_waitcnt lgkmcnt(5)
	v_mfma_f32_32x32x16_bf16 v[66:81], v[170:173], v[138:141], v[66:81]
	s_waitcnt lgkmcnt(4)
	v_mfma_f32_32x32x16_bf16 v[82:97], v[174:177], v[138:141], v[82:97]
	s_waitcnt lgkmcnt(3)
	v_mfma_f32_32x32x16_bf16 v[66:81], v[234:237], v[134:137], v[66:81]
	s_waitcnt lgkmcnt(2)
	v_mfma_f32_32x32x16_bf16 v[82:97], v[238:241], v[134:137], v[82:97]
	s_waitcnt lgkmcnt(1)
	v_mfma_f32_32x32x16_bf16 v[66:81], v[246:249], v[130:133], v[66:81]
	s_waitcnt lgkmcnt(0)
	v_mfma_f32_32x32x16_bf16 v[82:97], v[250:253], v[130:133], v[82:97]
; __device__ __forceinline__ void finishSM(f32x16& p0, f32x16& p1, float alpha, float& l_reg, bf16x8& pa0, bf16x8& pa1, bf16x8& pa2, bf16x8& pa3) {
; #pragma unroll
;     for (int r = 0; r < 16; ++r) p1[r] = __builtin_amdgcn_exp2f(p1[r]);
;     f32x4 s4 = (f32x4){p0[0], p0[1], p0[2], p0[3]} + (f32x4){p1[0], p1[1], p1[2], p1[3]};
; #pragma unroll
;     for (int r = 4; r < 16; r += 4) s4 += (f32x4){p0[r], p0[r + 1], p0[r + 2], p0[r + 3]} + (f32x4){p1[r], p1[r + 1], p1[r + 2], p1[r + 3]};
;     float ps = (s4[0] + s4[1]) + (s4[2] + s4[3]);
;     { auto rr = __builtin_amdgcn_permlane32_swap(__float_as_uint(ps), __float_as_uint(ps), false, false); ps = __uint_as_float(rr[0]) + __uint_as_float(rr[1]); }
;     l_reg = l_reg * alpha + ps;
;     ...
;     PK4(p0, 0, pa0); PK4(p0, 8, pa1); PK4(p1, 0, pa2); PK4(p1, 8, pa3);
;     ...
; }
; template <int VB>
; __device__ __forceinline__ void pv_tile(f32x16* o, int vb0, bf16x8 pa0, bf16x8 pa1, bf16x8 pa2, bf16x8 pa3) {
;     ...
;     PV_D0(0); PV_D0(1); PV_D0(2); PV_D0(3);
;     ...
; }
.Latta_531:
	s_add_i32 s12, s88, 0xffffff41
	s_cmp_le_i32 s12, s7
	s_cselect_b64 s[8:9], -1, 0
	s_cmp_gt_i32 s12, s7
	s_cbranch_scc1 .Latta_533
	v_exp_f32_e32 v114, v114
	v_exp_f32_e32 v115, v115
	v_exp_f32_e32 v116, v116
	v_exp_f32_e32 v117, v117
	v_exp_f32_e32 v118, v118
	v_exp_f32_e32 v119, v119
	v_exp_f32_e32 v120, v120
	v_exp_f32_e32 v121, v121
	v_exp_f32_e32 v122, v122
	v_exp_f32_e32 v123, v123
	v_exp_f32_e32 v124, v124
	v_exp_f32_e32 v125, v125
	v_exp_f32_e32 v126, v126
	v_exp_f32_e32 v127, v127
	v_exp_f32_e32 v128, v128
	v_exp_f32_e32 v129, v129
	v_pk_add_f32 v[162:163], v[100:101], v[116:117]
	v_pk_add_f32 v[164:165], v[98:99], v[114:115]
	v_pk_add_f32 v[166:167], v[118:119], v[102:103]
	v_pk_add_f32 v[168:169], v[120:121], v[104:105]
	v_pk_add_f32 v[164:165], v[166:167], v[164:165]
	v_pk_add_f32 v[162:163], v[168:169], v[162:163]
	v_pk_add_f32 v[166:167], v[124:125], v[108:109]
	v_pk_add_f32 v[168:169], v[122:123], v[106:107]
	v_pk_add_f32 v[162:163], v[166:167], v[162:163]
	v_pk_add_f32 v[164:165], v[168:169], v[164:165]
	v_pk_add_f32 v[166:167], v[126:127], v[110:111]
	v_pk_add_f32 v[168:169], v[128:129], v[112:113]
	v_pk_add_f32 v[164:165], v[166:167], v[164:165]
	v_pk_add_f32 v[162:163], v[168:169], v[162:163]
	s_nop 0
	v_pk_mov_b32 v[166:167], v[164:165], v[162:163] op_sel:[1,0]
	v_mov_b32_e32 v165, v163
	v_pk_add_f32 v[162:163], v[166:167], v[164:165]
	s_nop 0
	v_pk_add_f32 v[162:163], v[162:163], v[162:163] op_sel:[0,1] op_sel_hi:[1,0]
	s_nop 0
	v_mov_b32_e32 v163, v162
	s_nop 1
	v_permlane32_swap_b32_e32 v162, v163
	v_add_f32_e32 v242, v162, v163
	v_fmac_f32_e32 v242, v204, v230
	v_cvt_pk_bf16_f32 v162, v98, v99
	v_cvt_pk_bf16_f32 v163, v100, v101
	v_cvt_pk_bf16_f32 v164, v102, v103
	v_cvt_pk_bf16_f32 v165, v104, v105
	v_cvt_pk_bf16_f32 v166, v106, v107
	v_cvt_pk_bf16_f32 v167, v108, v109
	v_cvt_pk_bf16_f32 v168, v110, v111
	v_cvt_pk_bf16_f32 v169, v112, v113
	v_cvt_pk_bf16_f32 v170, v114, v115
	v_cvt_pk_bf16_f32 v171, v116, v117
	v_cvt_pk_bf16_f32 v172, v118, v119
	v_cvt_pk_bf16_f32 v173, v120, v121
	v_cvt_pk_bf16_f32 v174, v122, v123
	v_cvt_pk_bf16_f32 v175, v124, v125
	v_cvt_pk_bf16_f32 v176, v126, v127
	v_cvt_pk_bf16_f32 v177, v128, v129
	s_nop 0
	v_permlane32_swap_b32_e32 v162, v164
	v_permlane32_swap_b32_e32 v163, v165
	v_permlane32_swap_b32_e32 v166, v168
	v_permlane32_swap_b32_e32 v167, v169
	v_permlane32_swap_b32_e32 v170, v172
	v_permlane32_swap_b32_e32 v171, v173
	v_permlane32_swap_b32_e32 v174, v176
	v_permlane32_swap_b32_e32 v175, v177
	v_mov_b32_e32 v230, v242
.Latta_533:
	s_andn2_b64 vcc, exec, s[8:9]
	s_cbranch_vccnz .Latta_535
	ds_read_b64_tr_b16 v[234:235], v212 offset:0
	ds_read_b64_tr_b16 v[236:237], v212 offset:0x800
	ds_read_b64_tr_b16 v[238:239], v212 offset:0x1000
	ds_read_b64_tr_b16 v[240:241], v212 offset:0x1800
	ds_read_b64_tr_b16 v[246:247], v212 offset:0x2000
	ds_read_b64_tr_b16 v[248:249], v212 offset:0x2800
	ds_read_b64_tr_b16 v[250:251], v212 offset:0x3000
	ds_read_b64_tr_b16 v[252:253], v212 offset:0x3800
	s_waitcnt lgkmcnt(0)
	s_nop 0
	v_mfma_f32_32x32x16_bf16 v[34:49], v[162:165], v[234:237], v[34:49]
	ds_read_b64_tr_b16 v[234:235], v212 offset:0x200
	ds_read_b64_tr_b16 v[236:237], v212 offset:0xa00
	v_mfma_f32_32x32x16_bf16 v[34:49], v[166:169], v[238:241], v[34:49]
	ds_read_b64_tr_b16 v[238:239], v212 offset:0x1200
	ds_read_b64_tr_b16 v[240:241], v212 offset:0x1a00
	v_mfma_f32_32x32x16_bf16 v[34:49], v[170:173], v[246:249], v[34:49]
	ds_read_b64_tr_b16 v[246:247], v212 offset:0x2200
	ds_read_b64_tr_b16 v[248:249], v212 offset:0x2a00
	v_mfma_f32_32x32x16_bf16 v[34:49], v[174:177], v[250:253], v[34:49]
	ds_read_b64_tr_b16 v[250:251], v212 offset:0x3200
	ds_read_b64_tr_b16 v[252:253], v212 offset:0x3a00
	s_waitcnt lgkmcnt(0)
	v_mfma_f32_32x32x16_bf16 v[50:65], v[162:165], v[234:237], v[50:65]
	ds_read_b64_tr_b16 v[234:235], v212 offset:0x400
	ds_read_b64_tr_b16 v[236:237], v212 offset:0xc00
	v_mfma_f32_32x32x16_bf16 v[50:65], v[166:169], v[238:241], v[50:65]
	ds_read_b64_tr_b16 v[238:239], v212 offset:0x1400
	ds_read_b64_tr_b16 v[240:241], v212 offset:0x1c00
	v_mfma_f32_32x32x16_bf16 v[50:65], v[170:173], v[246:249], v[50:65]
	ds_read_b64_tr_b16 v[246:247], v212 offset:0x2400
	ds_read_b64_tr_b16 v[248:249], v212 offset:0x2c00
	v_mfma_f32_32x32x16_bf16 v[50:65], v[174:177], v[250:253], v[50:65]
	ds_read_b64_tr_b16 v[250:251], v212 offset:0x3400
	ds_read_b64_tr_b16 v[252:253], v212 offset:0x3c00
	s_waitcnt lgkmcnt(0)
	v_mfma_f32_32x32x16_bf16 v[18:33], v[162:165], v[234:237], v[18:33]
	ds_read_b64_tr_b16 v[234:235], v212 offset:0x600
	ds_read_b64_tr_b16 v[236:237], v212 offset:0xe00
	v_mfma_f32_32x32x16_bf16 v[18:33], v[166:169], v[238:241], v[18:33]
	ds_read_b64_tr_b16 v[238:239], v212 offset:0x1600
	ds_read_b64_tr_b16 v[240:241], v212 offset:0x1e00
	v_mfma_f32_32x32x16_bf16 v[18:33], v[170:173], v[246:249], v[18:33]
	ds_read_b64_tr_b16 v[246:247], v212 offset:0x2600
	ds_read_b64_tr_b16 v[248:249], v212 offset:0x2e00
	v_mfma_f32_32x32x16_bf16 v[18:33], v[174:177], v[250:253], v[18:33]
	ds_read_b64_tr_b16 v[250:251], v212 offset:0x3600
	ds_read_b64_tr_b16 v[252:253], v212 offset:0x3e00
	s_waitcnt lgkmcnt(0)
	v_mfma_f32_32x32x16_bf16 v[2:17], v[162:165], v[234:237], v[2:17]
	v_mfma_f32_32x32x16_bf16 v[2:17], v[166:169], v[238:241], v[2:17]
	v_mfma_f32_32x32x16_bf16 v[2:17], v[170:173], v[246:249], v[2:17]
	v_mfma_f32_32x32x16_bf16 v[2:17], v[174:177], v[250:253], v[2:17]

; #define LAS __attribute__((address_space(3)))
; template <int KB>
; __device__ __forceinline__ void qkt(f32x16& p0, f32x16& p1, lptr K_lds, int r32, int hi, const bf16x8* qr, const LAS float* blk) {
;     { const LAS f32x4* bp = (const LAS f32x4*)blk;
;       const f32x4 a0 = bp[0], a1 = bp[2], a2 = bp[4], a3 = bp[6], c0 = bp[8], c1 = bp[10], c2 = bp[12], c3 = bp[14];
;       p0 = (f32x16){a0[0], a0[1], a0[2], a0[3], a1[0], a1[1], a1[2], a1[3], a2[0], a2[1], a2[2], a2[3], a3[0], a3[1], a3[2], a3[3]};
;       p1 = (f32x16){c0[0], c0[1], c0[2], c0[3], c1[0], c1[1], c1[2], c1[3], c2[0], c2[1], c2[2], c2[3], c3[0], c3[1], c3[2], c3[3]}; }
;     lptr kb[4];
; #pragma unroll
;     for (int dd = 0; dd < 4; ++dd) kb[dd] = K_lds + KB * SHM_K + KSWZ(r32, (dd * 16 + hi * 8) * 2);
; #pragma unroll
;     for (int d0 = 0; d0 < 8; ++d0) { lptr a = kb[d0 & 3] + (d0 >> 2) * 128;
;         bf16x8 b0 = *(const LAS bf16x8*)(a);
;         bf16x8 b1 = *(const LAS bf16x8*)(a + 32 * 256);
;         p0 = __builtin_amdgcn_mfma_f32_32x32x16_bf16(b0, qr[d0], p0, 0, 0, 0);
;         p1 = __builtin_amdgcn_mfma_f32_32x32x16_bf16(b1, qr[d0], p1, 0, 0, 0); }
; }
; __device__ __forceinline__ void block(const BlockRef& cur, const BlockRef& nxt, lptr lds, Seam& S) {
;     ...
;     for (int t = 1; t + 1 < NT; t += 2) {
;         HALF_STEP(pB0, pB1, mnB, alB, pA0, pA1, alA, t, 1, 0, 0);
;         HALF_STEP(pA0, pA1, mnA, alA, pB0, pB1, alB, t + 1, 0, 1, 1);
.Latta_543:
	s_sub_i32 s12, s88, 63
	s_cmp_le_i32 s12, s7
	s_cselect_b64 s[10:11], -1, 0
	s_waitcnt lgkmcnt(0)
	s_barrier
	s_add_i32 s14, s6, 1
	s_cmp_lt_u32 s14, s95
	s_cselect_b64 s[70:71], -1, 0
	s_cbranch_scc0 .Latta_noload2
	s_add_u32 s14, s84, 0xc000
	s_addc_u32 s15, s85, 0
	s_add_u32 s16, s84, 0xe000
	s_addc_u32 s17, s85, 0
	s_add_u32 s18, s82, 0xc000
	s_addc_u32 s19, s83, 0
	s_add_u32 s20, s82, 0xe000
	s_addc_u32 s21, s83, 0
	v_lshl_add_u64 v[178:179], s[14:15], 0, v[198:199]
	v_lshl_add_u64 v[182:183], s[16:17], 0, v[198:199]
	v_lshl_add_u64 v[186:187], s[18:19], 0, v[198:199]
	v_lshl_add_u64 v[190:191], s[20:21], 0, v[198:199]
	global_load_dwordx4 v[178:181], v[178:179], off
	global_load_dwordx4 v[182:185], v[182:183], off
	global_load_dwordx4 v[186:189], v[186:187], off
	global_load_dwordx4 v[190:193], v[190:191], off
.Latta_noload2:
	s_cmp_gt_i32 s12, s7
	s_cbranch_scc1 .Latta_545
	ds_read_b128 v[98:101], v232 offset:256
	ds_read_b128 v[102:105], v232 offset:288
	ds_read_b128 v[106:109], v232 offset:320
	ds_read_b128 v[110:113], v232 offset:352
	ds_read_b128 v[162:165], v218 offset:32768
	ds_read_b128 v[166:169], v218 offset:40960
	ds_read_b128 v[114:117], v232 offset:384
	ds_read_b128 v[118:121], v232 offset:416
	ds_read_b128 v[122:125], v232 offset:448
	ds_read_b128 v[126:129], v232 offset:480
	ds_read_b128 v[170:173], v219 offset:32768
	ds_read_b128 v[174:177], v219 offset:40960
	ds_read_b128 v[234:237], v220 offset:32768
	ds_read_b128 v[238:241], v220 offset:40960
	ds_read_b128 v[246:249], v221 offset:32768
	s_waitcnt lgkmcnt(10)
	v_mfma_f32_32x32x16_bf16 v[98:113], v[162:165], v[158:161], v[98:113]
	ds_read_b128 v[250:253], v221 offset:40960
	s_waitcnt lgkmcnt(6)
	v_mfma_f32_32x32x16_bf16 v[114:129], v[166:169], v[158:161], v[114:129]
	ds_read_b128 v[162:165], v218 offset:32896
	s_waitcnt lgkmcnt(6)
	v_mfma_f32_32x32x16_bf16 v[98:113], v[170:173], v[154:157], v[98:113]
	ds_read_b128 v[166:169], v218 offset:41088
	s_waitcnt lgkmcnt(6)
	v_mfma_f32_32x32x16_bf16 v[114:129], v[174:177], v[154:157], v[114:129]
	ds_read_b128 v[170:173], v219 offset:32896
	s_waitcnt lgkmcnt(6)
	v_mfma_f32_32x32x16_bf16 v[98:113], v[234:237], v[150:153], v[98:113]
	ds_read_b128 v[174:177], v219 offset:41088
	s_waitcnt lgkmcnt(6)
	v_mfma_f32_32x32x16_bf16 v[114:129], v[238:241], v[150:153], v[114:129]
	ds_read_b128 v[234:237], v220 offset:32896
	s_waitcnt lgkmcnt(6)
	v_mfma_f32_32x32x16_bf16 v[98:113], v[246:249], v[146:149], v[98:113]
	ds_read_b128 v[238:241], v220 offset:41088
	s_waitcnt lgkmcnt(6)
	v_mfma_f32_32x32x16_bf16 v[114:129], v[250:253], v[146:149], v[114:129]
	ds_read_b128 v[246:249], v221 offset:32896
	s_waitcnt lgkmcnt(6)
	v_mfma_f32_32x32x16_bf16 v[98:113], v[162:165], v[142:145], v[98:113]
	ds_read_b128 v[250:253], v221 offset:41088
	s_waitcnt lgkmcnt(6)
	v_mfma_f32_32x32x16_bf16 v[114:129], v[166:169], v[142:145], v[114:129]
	s_waitcnt lgkmcnt(5)
	v_mfma_f32_32x32x16_bf16 v[98:113], v[170:173], v[138:141], v[98:113]
	s_waitcnt lgkmcnt(4)
	v_mfma_f32_32x32x16_bf16 v[114:129], v[174:177], v[138:141], v[114:129]
	s_waitcnt lgkmcnt(3)
	v_mfma_f32_32x32x16_bf16 v[98:113], v[234:237], v[134:137], v[98:113]
	s_waitcnt lgkmcnt(2)
	v_mfma_f32_32x32x16_bf16 v[114:129], v[238:241], v[134:137], v[114:129]
	s_waitcnt lgkmcnt(1)
	v_mfma_f32_32x32x16_bf16 v[98:113], v[246:249], v[130:133], v[98:113]
	s_waitcnt lgkmcnt(0)
	v_mfma_f32_32x32x16_bf16 v[114:129], v[250:253], v[130:133], v[114:129]
; __device__ __forceinline__ void finishSM(f32x16& p0, f32x16& p1, float alpha, float& l_reg, bf16x8& pa0, bf16x8& pa1, bf16x8& pa2, bf16x8& pa3) {
; #pragma unroll
;     for (int r = 0; r < 16; ++r) p1[r] = __builtin_amdgcn_exp2f(p1[r]);
;     f32x4 s4 = (f32x4){p0[0], p0[1], p0[2], p0[3]} + (f32x4){p1[0], p1[1], p1[2], p1[3]};
; #pragma unroll
;     for (int r = 4; r < 16; r += 4) s4 += (f32x4){p0[r], p0[r + 1], p0[r + 2], p0[r + 3]} + (f32x4){p1[r], p1[r + 1], p1[r + 2], p1[r + 3]};
;     float ps = (s4[0] + s4[1]) + (s4[2] + s4[3]);
;     { auto rr = __builtin_amdgcn_permlane32_swap(__float_as_uint(ps), __float_as_uint(ps), false, false); ps = __uint_as_float(rr[0]) + __uint_as_float(rr[1]); }
;     l_reg = l_reg * alpha + ps;
;     ...
;     PK4(p0, 0, pa0); PK4(p0, 8, pa1); PK4(p1, 0, pa2); PK4(p1, 8, pa3);
;     ...
; }
; template <int VB>
; __device__ __forceinline__ void pv_tile(f32x16* o, int vb0, bf16x8 pa0, bf16x8 pa1, bf16x8 pa2, bf16x8 pa3) {
;     ...
;     PV_D0(0); PV_D0(1); PV_D0(2); PV_D0(3);
;     ...
; }
.Latta_545:
	s_and_b64 vcc, exec, s[8:9]
	s_cbranch_vccnz .Latta_547
	v_exp_f32_e32 v82, v82
	v_exp_f32_e32 v83, v83
	v_exp_f32_e32 v84, v84
	v_exp_f32_e32 v85, v85
	v_exp_f32_e32 v86, v86
	v_exp_f32_e32 v87, v87
	v_exp_f32_e32 v88, v88
	v_exp_f32_e32 v89, v89
	v_exp_f32_e32 v90, v90
	v_exp_f32_e32 v91, v91
	v_exp_f32_e32 v92, v92
	v_exp_f32_e32 v93, v93
	v_exp_f32_e32 v94, v94
	v_exp_f32_e32 v95, v95
	v_exp_f32_e32 v96, v96
	v_exp_f32_e32 v97, v97
	v_pk_add_f32 v[162:163], v[68:69], v[84:85]
	v_pk_add_f32 v[164:165], v[66:67], v[82:83]
	v_pk_add_f32 v[166:167], v[70:71], v[86:87]
	v_pk_add_f32 v[168:169], v[72:73], v[88:89]
	v_pk_add_f32 v[164:165], v[166:167], v[164:165]
	v_pk_add_f32 v[162:163], v[168:169], v[162:163]
	v_pk_add_f32 v[166:167], v[76:77], v[92:93]
	v_pk_add_f32 v[168:169], v[74:75], v[90:91]
	v_pk_add_f32 v[162:163], v[166:167], v[162:163]
	v_pk_add_f32 v[164:165], v[168:169], v[164:165]
	v_pk_add_f32 v[166:167], v[78:79], v[94:95]
	v_pk_add_f32 v[168:169], v[80:81], v[96:97]
	v_pk_add_f32 v[164:165], v[166:167], v[164:165]
	v_pk_add_f32 v[162:163], v[168:169], v[162:163]
	s_nop 0
	v_pk_mov_b32 v[166:167], v[164:165], v[162:163] op_sel:[1,0]
	v_mov_b32_e32 v165, v163
	v_pk_add_f32 v[162:163], v[166:167], v[164:165]
	s_nop 0
	v_pk_add_f32 v[162:163], v[162:163], v[162:163] op_sel:[0,1] op_sel_hi:[1,0]
	s_nop 0
	v_mov_b32_e32 v163, v162
	s_nop 1
	v_permlane32_swap_b32_e32 v162, v163
	v_add_f32_e32 v234, v162, v163
	v_fmac_f32_e32 v234, v230, v233
	v_cvt_pk_bf16_f32 v162, v66, v67
	v_cvt_pk_bf16_f32 v163, v68, v69
	v_cvt_pk_bf16_f32 v164, v70, v71
	v_cvt_pk_bf16_f32 v165, v72, v73
	v_cvt_pk_bf16_f32 v166, v74, v75
	v_cvt_pk_bf16_f32 v167, v76, v77
	v_cvt_pk_bf16_f32 v168, v78, v79
	v_cvt_pk_bf16_f32 v169, v80, v81
	v_cvt_pk_bf16_f32 v170, v82, v83
	v_cvt_pk_bf16_f32 v171, v84, v85
	v_cvt_pk_bf16_f32 v172, v86, v87
	v_cvt_pk_bf16_f32 v173, v88, v89
	v_cvt_pk_bf16_f32 v174, v90, v91
	v_cvt_pk_bf16_f32 v175, v92, v93
	v_cvt_pk_bf16_f32 v176, v94, v95
	v_cvt_pk_bf16_f32 v177, v96, v97
	s_nop 0
	v_permlane32_swap_b32_e32 v162, v164
	v_permlane32_swap_b32_e32 v163, v165
	v_permlane32_swap_b32_e32 v166, v168
	v_permlane32_swap_b32_e32 v167, v169
	v_permlane32_swap_b32_e32 v170, v172
	v_permlane32_swap_b32_e32 v171, v173
	v_permlane32_swap_b32_e32 v174, v176
	v_permlane32_swap_b32_e32 v175, v177
	v_mov_b32_e32 v230, v234
	ds_read_b64_tr_b16 v[204:205], v212 offset:0x4000
	ds_read_b64_tr_b16 v[206:207], v212 offset:0x4800
	ds_read_b64_tr_b16 v[234:235], v212 offset:0x5000
	ds_read_b64_tr_b16 v[236:237], v212 offset:0x5800
	ds_read_b64_tr_b16 v[238:239], v212 offset:0x6000
	ds_read_b64_tr_b16 v[240:241], v212 offset:0x6800
	ds_read_b64_tr_b16 v[246:247], v212 offset:0x7000
	ds_read_b64_tr_b16 v[248:249], v212 offset:0x7800
	s_waitcnt lgkmcnt(0)
	s_nop 0
	v_mfma_f32_32x32x16_bf16 v[34:49], v[162:165], v[204:207], v[34:49]
	ds_read_b64_tr_b16 v[204:205], v212 offset:0x4200
	ds_read_b64_tr_b16 v[206:207], v212 offset:0x4a00
	v_mfma_f32_32x32x16_bf16 v[34:49], v[166:169], v[234:237], v[34:49]
	ds_read_b64_tr_b16 v[234:235], v212 offset:0x5200
	ds_read_b64_tr_b16 v[236:237], v212 offset:0x5a00
	v_mfma_f32_32x32x16_bf16 v[34:49], v[170:173], v[238:241], v[34:49]
	ds_read_b64_tr_b16 v[238:239], v212 offset:0x6200
	ds_read_b64_tr_b16 v[240:241], v212 offset:0x6a00
	v_mfma_f32_32x32x16_bf16 v[34:49], v[174:177], v[246:249], v[34:49]
	ds_read_b64_tr_b16 v[246:247], v212 offset:0x7200
	ds_read_b64_tr_b16 v[248:249], v212 offset:0x7a00
	s_waitcnt lgkmcnt(0)
	v_mfma_f32_32x32x16_bf16 v[50:65], v[162:165], v[204:207], v[50:65]
	ds_read_b64_tr_b16 v[204:205], v212 offset:0x4400
	ds_read_b64_tr_b16 v[206:207], v212 offset:0x4c00
	v_mfma_f32_32x32x16_bf16 v[50:65], v[166:169], v[234:237], v[50:65]
	ds_read_b64_tr_b16 v[234:235], v212 offset:0x5400
	ds_read_b64_tr_b16 v[236:237], v212 offset:0x5c00
	v_mfma_f32_32x32x16_bf16 v[50:65], v[170:173], v[238:241], v[50:65]
	ds_read_b64_tr_b16 v[238:239], v212 offset:0x6400
	ds_read_b64_tr_b16 v[240:241], v212 offset:0x6c00
	v_mfma_f32_32x32x16_bf16 v[50:65], v[174:177], v[246:249], v[50:65]
	ds_read_b64_tr_b16 v[246:247], v212 offset:0x7400
	ds_read_b64_tr_b16 v[248:249], v212 offset:0x7c00
	s_waitcnt lgkmcnt(0)
	v_mfma_f32_32x32x16_bf16 v[18:33], v[162:165], v[204:207], v[18:33]
	ds_read_b64_tr_b16 v[204:205], v212 offset:0x4600
	ds_read_b64_tr_b16 v[206:207], v212 offset:0x4e00
	v_mfma_f32_32x32x16_bf16 v[18:33], v[166:169], v[234:237], v[18:33]
	ds_read_b64_tr_b16 v[234:235], v212 offset:0x5600
	ds_read_b64_tr_b16 v[236:237], v212 offset:0x5e00
	v_mfma_f32_32x32x16_bf16 v[18:33], v[170:173], v[238:241], v[18:33]
	ds_read_b64_tr_b16 v[238:239], v212 offset:0x6600
	ds_read_b64_tr_b16 v[240:241], v212 offset:0x6e00
	v_mfma_f32_32x32x16_bf16 v[18:33], v[174:177], v[246:249], v[18:33]
	ds_read_b64_tr_b16 v[246:247], v212 offset:0x7600
	ds_read_b64_tr_b16 v[248:249], v212 offset:0x7e00
	s_waitcnt lgkmcnt(0)
	v_mfma_f32_32x32x16_bf16 v[2:17], v[162:165], v[204:207], v[2:17]
	v_mfma_f32_32x32x16_bf16 v[2:17], v[166:169], v[234:237], v[2:17]
	v_mfma_f32_32x32x16_bf16 v[2:17], v[170:173], v[238:241], v[2:17]
	v_mfma_f32_32x32x16_bf16 v[2:17], v[174:177], v[246:249], v[2:17]
.Latta_547:
	s_andn2_b64 vcc, exec, s[10:11]
	v_mov_b32_e32 v204, 1.0
	s_cbranch_vccnz .Latta_555
